# ret_A writes ABUF/KDT fragment-major + hand-written retention scan (rolling fragment reloads, 1 KiB-contiguous loads); plus earlier row-phase and attn_sample rewrites
# speedup vs baseline: 1.0641x; 1.0315x over previous
.LBB0_1233:
	s_or_b64 exec, exec, s[0:1]
	v_mov_b32_e32 v80, v198
	s_and_b64 vcc, exec, s[54:55]
	s_waitcnt lgkmcnt(0)
	s_barrier
	s_cbranch_vccz .LBB0_1260
	v_readlane_b32 s0, v254, 29
	s_ashr_i32 s49, s48, 31
	s_lshl_b32 s7, s2, 7
	v_add_u32_e32 v8, 0x200, v80
	v_add_u32_e32 v16, 0x400, v80
	v_add_u32_e32 v24, 0x600, v80
	v_add_u32_e32 v32, 0x800, v80
	v_add_u32_e32 v40, 0xa00, v80
	v_add_u32_e32 v48, 0xc00, v80
	v_add_u32_e32 v56, 0xe00, v80
	s_and_b32 s6, s0, 0x300
	s_lshl_b64 s[0:1], s[48:49], 12
	s_and_b32 s7, s7, 0xf80
	v_lshlrev_b32_e32 v0, 3, v80
	v_ashrrev_i32_e32 v64, 5, v80
	v_ashrrev_i32_e32 v66, 5, v8
	v_ashrrev_i32_e32 v68, 5, v16
	v_ashrrev_i32_e32 v70, 5, v24
	v_ashrrev_i32_e32 v72, 5, v32
	v_ashrrev_i32_e32 v74, 5, v40
	v_ashrrev_i32_e32 v76, 5, v48
	v_ashrrev_i32_e32 v78, 5, v56
	s_or_b32 s0, s0, s7
	v_and_b32_e32 v86, 0xf8, v0
	v_ashrrev_i32_e32 v65, 31, v64
	v_ashrrev_i32_e32 v67, 31, v66
	v_ashrrev_i32_e32 v69, 31, v68
	v_ashrrev_i32_e32 v71, 31, v70
	v_ashrrev_i32_e32 v73, 31, v72
	v_ashrrev_i32_e32 v75, 31, v74
	v_ashrrev_i32_e32 v77, 31, v76
	v_ashrrev_i32_e32 v79, 31, v78
	v_or_b32_e32 v2, s6, v86
	v_lshl_add_u64 v[0:1], s[0:1], 0, v[64:65]
	v_lshl_add_u64 v[8:9], s[0:1], 0, v[66:67]
	v_lshl_add_u64 v[16:17], s[0:1], 0, v[68:69]
	v_lshl_add_u64 v[24:25], s[0:1], 0, v[70:71]
	v_lshl_add_u64 v[32:33], s[0:1], 0, v[72:73]
	v_lshl_add_u64 v[40:41], s[0:1], 0, v[74:75]
	v_lshl_add_u64 v[48:49], s[0:1], 0, v[76:77]
	v_lshl_add_u64 v[56:57], s[0:1], 0, v[78:79]
	v_lshlrev_b64 v[0:1], 11, v[0:1]
	v_lshlrev_b32_e32 v58, 1, v2
	v_lshlrev_b64 v[8:9], 11, v[8:9]
	v_lshlrev_b64 v[16:17], 11, v[16:17]
	v_lshlrev_b64 v[24:25], 11, v[24:25]
	v_lshlrev_b64 v[32:33], 11, v[32:33]
	v_lshlrev_b64 v[40:41], 11, v[40:41]
	v_lshlrev_b64 v[48:49], 11, v[48:49]
	v_lshlrev_b64 v[56:57], 11, v[56:57]
	v_or_b32_e32 v0, v0, v58
	v_or_b32_e32 v8, v8, v58
	v_or_b32_e32 v16, v16, v58
	v_or_b32_e32 v24, v24, v58
	v_or_b32_e32 v32, v32, v58
	v_or_b32_e32 v40, v40, v58
	v_or_b32_e32 v48, v48, v58
	v_or_b32_e32 v56, v56, v58
	v_lshl_add_u64 v[2:3], s[30:31], 0, v[0:1]
	v_lshl_add_u64 v[4:5], s[34:35], 0, v[0:1]
	v_lshl_add_u64 v[10:11], s[30:31], 0, v[8:9]
	v_lshl_add_u64 v[12:13], s[34:35], 0, v[8:9]
	v_lshl_add_u64 v[18:19], s[30:31], 0, v[16:17]
	v_lshl_add_u64 v[20:21], s[34:35], 0, v[16:17]
	v_lshl_add_u64 v[26:27], s[30:31], 0, v[24:25]
	v_lshl_add_u64 v[28:29], s[34:35], 0, v[24:25]
	v_lshl_add_u64 v[34:35], s[30:31], 0, v[32:33]
	v_lshl_add_u64 v[36:37], s[34:35], 0, v[32:33]
	v_lshl_add_u64 v[42:43], s[30:31], 0, v[40:41]
	v_lshl_add_u64 v[44:45], s[34:35], 0, v[40:41]
	v_lshl_add_u64 v[50:51], s[30:31], 0, v[48:49]
	v_lshl_add_u64 v[52:53], s[34:35], 0, v[48:49]
	v_lshl_add_u64 v[58:59], s[30:31], 0, v[56:57]
	v_lshl_add_u64 v[60:61], s[34:35], 0, v[56:57]
	global_load_dwordx4 v[0:3], v[2:3], off
	s_nop 0
	global_load_dwordx4 v[4:7], v[4:5], off
	s_nop 0
	global_load_dwordx4 v[8:11], v[10:11], off
	s_nop 0
	global_load_dwordx4 v[12:15], v[12:13], off
	s_nop 0
	global_load_dwordx4 v[16:19], v[18:19], off
	s_nop 0
	global_load_dwordx4 v[20:23], v[20:21], off
	s_nop 0
	global_load_dwordx4 v[24:27], v[26:27], off
	s_nop 0
	global_load_dwordx4 v[28:31], v[28:29], off
	s_nop 0
	global_load_dwordx4 v[32:35], v[34:35], off
	s_nop 0
	global_load_dwordx4 v[36:39], v[36:37], off
	s_nop 0
	global_load_dwordx4 v[40:43], v[42:43], off
	s_nop 0
	global_load_dwordx4 v[44:47], v[44:45], off
	s_nop 0
	global_load_dwordx4 v[48:51], v[50:51], off
	s_nop 0
	global_load_dwordx4 v[52:55], v[52:53], off
	s_nop 0
	global_load_dwordx4 v[56:59], v[58:59], off
	s_nop 0
	global_load_dwordx4 v[60:63], v[60:61], off
	v_bfe_u32 v205, v80, 4, 2
	v_and_b32_e32 v81, 15, v80
	v_ashrrev_i32_e32 v82, 6, v80
	v_lshl_or_b32 v84, v82, 4, v81
	s_movk_i32 s1, 0x210
	v_lshlrev_b32_e32 v137, 2, v205
	s_add_i32 s0, 0, 0x10800
	v_lshlrev_b32_e32 v106, 4, v205
	v_mul_lo_u32 v87, v84, s1
	v_mul_u32_u24_e32 v81, 0x210, v81
	v_cmp_lt_i32_e64 s[8:9], v84, v137
	v_lshlrev_b32_e32 v83, 1, v86
	v_add3_u32 v87, 0, v87, v106
	v_add3_u32 v106, s0, v106, v81
	v_writelane_b32 v254, s8, 23
	v_sub_u32_e32 v81, v84, v137
	v_add_u32_e32 v85, 0, v83
	v_add_u32_e32 v83, s0, v83
	v_mul_lo_u32 v91, v64, s1
	v_mul_lo_u32 v93, v66, s1
	v_mul_lo_u32 v95, v68, s1
	v_mul_lo_u32 v97, v70, s1
	v_mul_lo_u32 v99, v72, s1
	v_mul_lo_u32 v101, v74, s1
	v_mul_lo_u32 v103, v76, s1
	v_mul_lo_u32 v105, v78, s1
	v_writelane_b32 v254, s9, 24
	v_cvt_f32_i32_e32 v107, v81
	v_cmp_gt_i32_e64 s[8:9], v84, v137
	v_xad_u32 v81, v137, -1, v84
	v_add_u32_e32 v90, v85, v91
	v_add_u32_e32 v91, v83, v91
	v_add_u32_e32 v92, v85, v93
	v_add_u32_e32 v93, v83, v93
	v_add_u32_e32 v94, v85, v95
	v_add_u32_e32 v95, v83, v95
	v_add_u32_e32 v96, v85, v97
	v_add_u32_e32 v97, v83, v97
	v_add_u32_e32 v98, v85, v99
	v_add_u32_e32 v99, v83, v99
	v_add_u32_e32 v100, v85, v101
	v_add_u32_e32 v101, v83, v101
	v_add_u32_e32 v102, v85, v103
	v_add_u32_e32 v103, v83, v103
	v_add_u32_e32 v104, v85, v105
	v_add_u32_e32 v105, v83, v105
	v_writelane_b32 v254, s8, 30
	v_cvt_f32_i32_e32 v108, v81
	v_or_b32_e32 v81, 3, v137
	v_or_b32_e32 v83, 2, v137
	v_writelane_b32 v254, s9, 31
	v_sub_u32_e32 v85, v84, v83
	v_cmp_lt_i32_e64 s[8:9], v84, v81
	v_cvt_f32_i32_e32 v109, v85
	v_sub_u32_e32 v81, v84, v81
	v_writelane_b32 v254, s8, 44
	v_or_b32_e32 v85, 16, v137
	v_cvt_f32_i32_e32 v110, v81
	v_writelane_b32 v254, s9, 45
	v_cmp_lt_i32_e64 s[8:9], v84, v83
	v_or_b32_e32 v83, 17, v137
	v_sub_u32_e32 v81, v84, v85
	v_cvt_f32_i32_e32 v111, v81
	v_sub_u32_e32 v81, v84, v83
	v_or_b32_e32 v208, 18, v137
	v_cvt_f32_i32_e32 v112, v81
	v_or_b32_e32 v207, 19, v137
	v_sub_u32_e32 v81, v84, v208
	v_cvt_f32_i32_e32 v113, v81
	v_sub_u32_e32 v81, v84, v207
	v_or_b32_e32 v210, 32, v137
	v_cvt_f32_i32_e32 v114, v81
	v_or_b32_e32 v209, 33, v137
	v_sub_u32_e32 v81, v84, v210
	v_cvt_f32_i32_e32 v115, v81
	v_sub_u32_e32 v81, v84, v209
	v_or_b32_e32 v213, 34, v137
	v_cvt_f32_i32_e32 v116, v81
	v_or_b32_e32 v212, 35, v137
	v_sub_u32_e32 v81, v84, v213
	v_cvt_f32_i32_e32 v117, v81
	v_sub_u32_e32 v81, v84, v212
	v_or_b32_e32 v215, 48, v137
	v_cvt_f32_i32_e32 v118, v81
	v_or_b32_e32 v214, 49, v137
	v_sub_u32_e32 v81, v84, v215
	v_cvt_f32_i32_e32 v119, v81
	v_sub_u32_e32 v81, v84, v214
	v_or_b32_e32 v217, 50, v137
	v_cvt_f32_i32_e32 v120, v81
	v_or_b32_e32 v216, 51, v137
	v_sub_u32_e32 v81, v84, v217
	v_cvt_f32_i32_e32 v121, v81
	v_sub_u32_e32 v81, v84, v216
	v_or_b32_e32 v219, 64, v137
	v_cvt_f32_i32_e32 v122, v81
	v_or_b32_e32 v218, 0x41, v137
	v_sub_u32_e32 v81, v84, v219
	v_cvt_f32_i32_e32 v123, v81
	v_sub_u32_e32 v81, v84, v218
	v_or_b32_e32 v221, 0x42, v137
	v_cvt_f32_i32_e32 v124, v81
	v_or_b32_e32 v220, 0x43, v137
	v_sub_u32_e32 v81, v84, v221
	v_cvt_f32_i32_e32 v125, v81
	v_sub_u32_e32 v81, v84, v220
	v_or_b32_e32 v223, 0x50, v137
	v_cvt_f32_i32_e32 v126, v81
	v_or_b32_e32 v222, 0x51, v137
	v_sub_u32_e32 v81, v84, v223
	v_cvt_f32_i32_e32 v127, v81
	v_sub_u32_e32 v81, v84, v222
	v_or_b32_e32 v225, 0x52, v137
	v_cvt_f32_i32_e32 v128, v81
	v_or_b32_e32 v224, 0x53, v137
	v_sub_u32_e32 v81, v84, v225
	v_cvt_f32_i32_e32 v129, v81
	v_sub_u32_e32 v81, v84, v224
	v_or_b32_e32 v227, 0x60, v137
	v_cvt_f32_i32_e32 v130, v81
	v_or_b32_e32 v226, 0x61, v137
	v_sub_u32_e32 v81, v84, v227
	v_cvt_f32_i32_e32 v131, v81
	v_sub_u32_e32 v81, v84, v226
	v_or_b32_e32 v229, 0x62, v137
	v_cvt_f32_i32_e32 v132, v81
	v_or_b32_e32 v228, 0x63, v137
	v_sub_u32_e32 v81, v84, v229
	v_cvt_f32_i32_e32 v133, v81
	v_sub_u32_e32 v81, v84, v228
	v_or_b32_e32 v231, 0x70, v137
	v_cvt_f32_i32_e32 v134, v81
	v_or_b32_e32 v230, 0x71, v137
	v_sub_u32_e32 v81, v84, v231
	v_cvt_f32_i32_e32 v135, v81
	v_sub_u32_e32 v81, v84, v230
	v_or_b32_e32 v232, 0x72, v137
	v_cmp_lt_i32_e64 s[6:7], -1, v82
	v_cmp_lt_i32_e64 s[16:17], 0, v82
	v_cmp_lt_i32_e64 s[18:19], 1, v82
	v_cmp_lt_i32_e64 s[20:21], 2, v82
	v_cmp_lt_i32_e64 s[22:23], 3, v82
	v_cmp_lt_i32_e64 s[24:25], 4, v82
	v_cmp_lt_i32_e64 s[26:27], 5, v82
	v_cmp_lt_i32_e64 s[28:29], 6, v82
	v_cvt_f32_i32_e32 v136, v81
	v_or_b32_e32 v82, 0x73, v137
	v_sub_u32_e32 v81, v84, v232
	v_and_b32_e32 v206, 0xff, v80
	v_and_b32_e32 v80, -8, v64
	v_cvt_f32_i32_e32 v137, v81
	v_sub_u32_e32 v81, v84, v82
	v_cvt_f32_i32_e32 v138, v81
	v_sub_u32_e32 v81, 0x7f, v80
	v_cvt_f32_i32_e32 v139, v81
	v_or_b32_e32 v81, 1, v80
	v_sub_u32_e32 v81, 0x7f, v81
	v_cvt_f32_i32_e32 v140, v81
	v_or_b32_e32 v81, 2, v80
	v_sub_u32_e32 v81, 0x7f, v81
	v_cvt_f32_i32_e32 v141, v81
	v_or_b32_e32 v81, 3, v80
	v_sub_u32_e32 v81, 0x7f, v81
	v_cvt_f32_i32_e32 v142, v81
	v_or_b32_e32 v81, 4, v80
	v_sub_u32_e32 v81, 0x7f, v81
	v_cvt_f32_i32_e32 v143, v81
	v_or_b32_e32 v81, 5, v80
	v_sub_u32_e32 v81, 0x7f, v81
	v_cvt_f32_i32_e32 v144, v81
	v_or_b32_e32 v81, 6, v80
	v_sub_u32_e32 v81, 0x7f, v81
	v_writelane_b32 v254, s8, 25
	v_cvt_f32_i32_e32 v145, v81
	v_or_b32_e32 v81, 7, v64
	v_lshl_add_u32 v88, v206, 1, s0
	v_mul_lo_u32 v89, v80, s1
	v_writelane_b32 v254, s9, 26
	v_mul_lo_u32 v233, v81, s1
	v_cmp_lt_i32_e64 s[0:1], v84, v207
	v_sub_u32_e32 v81, 0x7f, v81
	s_lshl_b64 s[8:9], s[2:3], 16
	v_writelane_b32 v254, s0, 51
	v_cvt_f32_i32_e32 v146, v81
	v_ashrrev_i32_e32 v81, 31, v80
	v_writelane_b32 v254, s1, 52
	v_cmp_lt_i32_e64 s[0:1], v84, v208
	v_cmp_lt_i32_e64 s[80:81], v84, v82
	v_lshl_or_b32 v82, v206, 8, s8
	v_writelane_b32 v254, s0, 63
	v_sub_u32_e32 v147, 0x6f, v80
	v_sub_u32_e32 v148, 0x6e, v80
	v_writelane_b32 v255, s1, 0
	v_cmp_lt_i32_e64 s[0:1], v84, v83
	v_mov_b32_e32 v83, s9
	v_sub_u32_e32 v149, 0x6d, v80
	v_sub_u32_e32 v150, 0x6c, v80
	v_sub_u32_e32 v151, 0x6b, v80
	v_sub_u32_e32 v152, 0x6a, v80
	v_sub_u32_e32 v153, 0x69, v80
	v_sub_u32_e32 v154, 0x68, v80
	v_sub_u32_e32 v155, 0x5f, v80
	v_sub_u32_e32 v156, 0x5e, v80
	v_sub_u32_e32 v157, 0x5d, v80
	v_sub_u32_e32 v158, 0x5c, v80
	v_sub_u32_e32 v159, 0x5b, v80
	v_sub_u32_e32 v160, 0x5a, v80
	v_sub_u32_e32 v161, 0x59, v80
	v_sub_u32_e32 v162, 0x58, v80
	v_sub_u32_e32 v163, 0x4f, v80
	v_sub_u32_e32 v164, 0x4e, v80
	v_sub_u32_e32 v165, 0x4d, v80
	v_sub_u32_e32 v166, 0x4c, v80
	v_sub_u32_e32 v167, 0x4b, v80
	v_sub_u32_e32 v168, 0x4a, v80
	v_sub_u32_e32 v169, 0x49, v80
	v_sub_u32_e32 v170, 0x48, v80
	v_sub_u32_e32 v171, 63, v80
	v_sub_u32_e32 v172, 62, v80
	v_sub_u32_e32 v173, 61, v80
	v_sub_u32_e32 v174, 60, v80
	v_sub_u32_e32 v175, 59, v80
	v_sub_u32_e32 v176, 58, v80
	v_sub_u32_e32 v177, 57, v80
	v_sub_u32_e32 v178, 56, v80
	v_sub_u32_e32 v179, 47, v80
	v_sub_u32_e32 v180, 46, v80
	v_sub_u32_e32 v181, 45, v80
	v_sub_u32_e32 v182, 44, v80
	v_sub_u32_e32 v183, 43, v80
	v_sub_u32_e32 v184, 42, v80
	v_sub_u32_e32 v185, 41, v80
	v_sub_u32_e32 v186, 40, v80
	v_sub_u32_e32 v187, 31, v80
	v_sub_u32_e32 v188, 30, v80
	v_sub_u32_e32 v189, 29, v80
	v_sub_u32_e32 v190, 28, v80
	v_sub_u32_e32 v191, 27, v80
	v_sub_u32_e32 v192, 26, v80
	v_sub_u32_e32 v193, 25, v80
	v_sub_u32_e32 v194, 24, v80
	v_sub_u32_e32 v195, 15, v80
	v_sub_u32_e32 v196, 14, v80
	v_sub_u32_e32 v197, 13, v80
	v_sub_u32_e32 v200, 12, v80
	v_sub_u32_e32 v201, 11, v80
	v_sub_u32_e32 v202, 10, v80
	v_sub_u32_e32 v203, 9, v80
	v_sub_u32_e32 v204, 8, v80
	v_writelane_b32 v255, s0, 1
	v_lshl_add_u64 v[80:81], v[80:81], 1, v[82:83]
	v_lshl_add_u64 v[80:81], s[94:95], 0, v[80:81]
	v_writelane_b32 v255, s1, 2
	v_cmp_lt_i32_e64 s[0:1], v84, v85
	s_mov_b64 s[8:9], 0x28402880
	v_ashrrev_i32_e32 v85, 31, v84
	v_writelane_b32 v255, s0, 3
	v_lshl_add_u64 v[80:81], v[80:81], 0, s[8:9]
	s_lshl_b64 s[8:9], s[2:3], 15
	v_lshlrev_b64 v[82:83], 8, v[84:85]
	v_cvt_f32_i32_e32 v147, v147
	v_cvt_f32_i32_e32 v148, v148
	v_cvt_f32_i32_e32 v149, v149
	v_cvt_f32_i32_e32 v150, v150
	v_cvt_f32_i32_e32 v151, v151
	v_cvt_f32_i32_e32 v152, v152
	v_cvt_f32_i32_e32 v153, v153
	v_cvt_f32_i32_e32 v154, v154
	v_cvt_f32_i32_e32 v155, v155
	v_cvt_f32_i32_e32 v156, v156
	v_cvt_f32_i32_e32 v157, v157
	v_cvt_f32_i32_e32 v158, v158
	v_cvt_f32_i32_e32 v159, v159
	v_cvt_f32_i32_e32 v160, v160
	v_cvt_f32_i32_e32 v161, v161
	v_cvt_f32_i32_e32 v162, v162
	v_cvt_f32_i32_e32 v163, v163
	v_cvt_f32_i32_e32 v164, v164
	v_cvt_f32_i32_e32 v165, v165
	v_cvt_f32_i32_e32 v166, v166
	v_cvt_f32_i32_e32 v167, v167
	v_cvt_f32_i32_e32 v168, v168
	v_cvt_f32_i32_e32 v169, v169
	v_cvt_f32_i32_e32 v170, v170
	v_cvt_f32_i32_e32 v171, v171
	v_cvt_f32_i32_e32 v172, v172
	v_cvt_f32_i32_e32 v173, v173
	v_cvt_f32_i32_e32 v174, v174
	v_cvt_f32_i32_e32 v175, v175
	v_cvt_f32_i32_e32 v176, v176
	v_cvt_f32_i32_e32 v177, v177
	v_cvt_f32_i32_e32 v178, v178
	v_cvt_f32_i32_e32 v179, v179
	v_cvt_f32_i32_e32 v180, v180
	v_cvt_f32_i32_e32 v181, v181
	v_cvt_f32_i32_e32 v182, v182
	v_cvt_f32_i32_e32 v183, v183
	v_cvt_f32_i32_e32 v184, v184
	v_cvt_f32_i32_e32 v185, v185
	v_cvt_f32_i32_e32 v186, v186
	v_cvt_f32_i32_e32 v187, v187
	v_cvt_f32_i32_e32 v188, v188
	v_cvt_f32_i32_e32 v189, v189
	v_cvt_f32_i32_e32 v190, v190
	v_cvt_f32_i32_e32 v191, v191
	v_cvt_f32_i32_e32 v192, v192
	v_cvt_f32_i32_e32 v193, v193
	v_cvt_f32_i32_e32 v194, v194
	v_cvt_f32_i32_e32 v195, v195
	v_cvt_f32_i32_e32 v196, v196
	v_cvt_f32_i32_e32 v197, v197
	v_cvt_f32_i32_e32 v200, v200
	v_cvt_f32_i32_e32 v201, v201
	v_cvt_f32_i32_e32 v202, v202
	v_cvt_f32_i32_e32 v203, v203
	v_cvt_f32_i32_e32 v204, v204
	v_writelane_b32 v255, s1, 4
	v_cmp_lt_i32_e64 s[0:1], v84, v212
	v_lshl_add_u64 v[82:83], s[8:9], 0, v[82:83]
	v_lshl_or_b32 v82, v205, 3, v82
	v_writelane_b32 v255, s0, 5
	v_add_u32_e32 v211, 0xe700, v89
	v_add_u32_e32 v234, 0x2310, v89
	v_add_u32_e32 v235, 0x4410, v89
	v_add_u32_e32 v236, 0x6510, v89
	v_add_u32_e32 v237, 0x8610, v89
	v_add_u32_e32 v238, 0xa710, v89
	v_add_u32_e32 v239, 0xc810, v89
	v_add_u32_e32 v240, 0xe910, v89
	v_writelane_b32 v255, s1, 6
	s_add_i32 s0, s2, s96
	v_lshl_add_u64 v[82:83], s[94:95], 0, v[82:83]
	s_mov_b64 s[8:9], 0x27402880
	v_cmp_lt_i32_e64 s[40:41], v84, v213
	v_cmp_lt_i32_e64 s[42:43], v84, v209
	v_cmp_lt_i32_e64 s[46:47], v84, v210
	v_cmp_lt_i32_e64 s[48:49], v84, v216
	v_cmp_lt_i32_e64 s[50:51], v84, v217
	v_cmp_lt_i32_e64 s[52:53], v84, v214
	v_cmp_lt_i32_e64 s[54:55], v84, v215
	v_cmp_lt_i32_e64 s[56:57], v84, v220
	v_cmp_lt_i32_e64 s[58:59], v84, v221
	v_cmp_lt_i32_e64 s[60:61], v84, v218
	v_cmp_lt_i32_e64 s[62:63], v84, v219
	v_cmp_lt_i32_e64 s[64:65], v84, v224
	v_cmp_lt_i32_e64 s[66:67], v84, v225
	v_cmp_lt_i32_e64 s[68:69], v84, v222
	v_cmp_lt_i32_e64 s[70:71], v84, v223
	v_cmp_lt_i32_e64 s[72:73], v84, v228
	v_cmp_lt_i32_e64 s[74:75], v84, v229
	v_cmp_lt_i32_e64 s[76:77], v84, v226
	v_cmp_lt_i32_e64 s[78:79], v84, v227
	v_cmp_lt_i32_e64 s[82:83], v84, v232
	s_lshl_b32 s33, s0, 3
	s_lshl_b32 s0, s0, 7
	v_lshl_add_u64 v[82:83], v[82:83], 0, s[8:9]
	s_lshl_b32 s1, s96, 7
	v_add_u32_e32 v85, v88, v233
	v_add_u32_e32 v205, v88, v234
	v_add_u32_e32 v206, v88, v235
	v_add_u32_e32 v207, v88, v236
	v_add_u32_e32 v208, v88, v237
	v_add_u32_e32 v209, v88, v238
	v_add_u32_e32 v210, v88, v239
	v_add_u32_e32 v211, v88, v211
	v_add_u32_e32 v212, v88, v240
	v_mov_b32_e32 v213, 0xbb80402b
	v_mov_b32_e32 v214, 0xbc0080ac
	s_mov_b32 s36, s2
	v_cmp_lt_i32_e64 s[84:85], v84, v230
	v_cmp_lt_i32_e64 s[86:87], v84, v231
	s_lshl_b64 s[14:15], s[90:91], 16
	s_lshl_b64 s[10:11], s[90:91], 15
	v_lshrrev_b32_e32 v82, 6, v198
	v_bfe_u32 v83, v198, 4, 2
	v_and_b32_e32 v80, 15, v198
	v_lshlrev_b32_e32 v82, 12, v82
	v_lshrrev_b32_e32 v81, 1, v83
	v_lshl_add_u32 v82, v81, 8, v82
	v_lshl_add_u32 v82, v80, 4, v82
	v_and_b32_e32 v81, 1, v83
	v_lshl_add_u32 v82, v81, 3, v82
	s_lshl_b32 s8, s2, 15
	s_add_u32 s8, s8, 0x27403000
	v_add_u32_e32 v82, s8, v82
	v_mov_b32_e32 v83, 0
	v_lshl_add_u64 v[82:83], s[94:95], 0, v[82:83]
	v_bfe_u32 v80, v198, 5, 3
	v_lshlrev_b32_e32 v80, 13, v80
	v_bfe_u32 v81, v198, 4, 1
	v_lshl_add_u32 v80, v81, 12, v80
	v_and_b32_e32 v81, 15, v198
	v_lshl_add_u32 v80, v81, 4, v80
	v_lshrrev_b32_e32 v81, 8, v198
	v_lshl_add_u32 v80, v81, 8, v80
	s_lshl_b32 s8, s2, 16
	s_add_u32 s8, s8, 0x28403000
	v_add_u32_e32 v80, s8, v80
	v_mov_b32_e32 v81, 0
	v_lshl_add_u64 v[80:81], s[94:95], 0, v[80:81]
	s_branch .LBB0_1236
.LBB0_1235:
	s_or_b64 exec, exec, vcc
	v_cvt_pk_bf16_f32 v216, v215, v216
	v_cvt_pk_bf16_f32 v217, v217, v218
	v_add_u32_e32 v215, v88, v89
	global_store_dwordx2 v[82:83], v[216:217], off offset:1536
	ds_read_u16 v216, v215
	v_mul_f32_e32 v217, v84, v139
	v_mul_f32_e32 v217, 0x3fb8aa3b, v217
	v_exp_f32_e32 v217, v217
	v_mul_f32_e32 v218, v84, v140
	s_waitcnt lgkmcnt(0)
	v_lshlrev_b32_e32 v216, 16, v216
	v_mul_f32_e32 v218, 0x3fb8aa3b, v218
	v_mul_f32_e32 v216, v217, v216
	ds_read_u16 v217, v215 offset:528
	v_exp_f32_e32 v218, v218
	v_mul_f32_e32 v219, v84, v141
	v_mul_f32_e32 v219, 0x3fb8aa3b, v219
	v_exp_f32_e32 v219, v219
	s_waitcnt lgkmcnt(0)
	v_lshlrev_b32_e32 v217, 16, v217
	v_mul_f32_e32 v217, v218, v217
	ds_read_u16 v218, v215 offset:1056
	v_mul_f32_e32 v220, v84, v142
	v_mul_f32_e32 v220, 0x3fb8aa3b, v220
	v_exp_f32_e32 v220, v220
	v_mul_f32_e32 v221, v84, v143
	s_waitcnt lgkmcnt(0)
	v_lshlrev_b32_e32 v218, 16, v218
	v_mul_f32_e32 v218, v219, v218
	ds_read_u16 v219, v215 offset:1584
	v_mul_f32_e32 v221, 0x3fb8aa3b, v221
	v_exp_f32_e32 v221, v221
	v_mul_f32_e32 v222, v84, v144
	v_mul_f32_e32 v222, 0x3fb8aa3b, v222
	s_waitcnt lgkmcnt(0)
	v_lshlrev_b32_e32 v219, 16, v219
	v_mul_f32_e32 v219, v220, v219
	ds_read_u16 v220, v215 offset:2112
	v_exp_f32_e32 v222, v222
	v_mul_f32_e32 v223, v84, v145
	v_mul_f32_e32 v223, 0x3fb8aa3b, v223
	v_exp_f32_e32 v223, v223
	s_waitcnt lgkmcnt(0)
	v_lshlrev_b32_e32 v220, 16, v220
	v_mul_f32_e32 v220, v221, v220
	ds_read_u16 v221, v215 offset:2640
	v_mul_f32_e32 v224, v84, v146
	v_mul_f32_e32 v224, 0x3fb8aa3b, v224
	v_exp_f32_e32 v224, v224
	v_readlane_b32 s38, v254, 27
	s_waitcnt lgkmcnt(0)
	v_lshlrev_b32_e32 v221, 16, v221
	v_mul_f32_e32 v221, v222, v221
	ds_read_u16 v222, v215 offset:3168
	s_add_i32 s33, s33, s38
	s_add_i32 s0, s0, s1
	v_lshl_add_u64 v[82:83], v[82:83], 0, s[10:11]
	s_andn2_b64 vcc, exec, s[8:9]
	s_waitcnt lgkmcnt(0)
	v_lshlrev_b32_e32 v222, 16, v222
	v_mul_f32_e32 v222, v223, v222
	ds_read_u16 v223, v85
	v_cvt_pk_bf16_f32 v216, v216, v217
	v_cvt_pk_bf16_f32 v217, v218, v219
	v_cvt_pk_bf16_f32 v218, v220, v221
	v_mul_f32_e32 v220, v84, v150
	s_waitcnt lgkmcnt(0)
	v_lshlrev_b32_e32 v223, 16, v223
	v_mul_f32_e32 v223, v224, v223
	v_cvt_pk_bf16_f32 v219, v222, v223
	global_store_dwordx4 v[80:81], v[216:219], off offset:-2048
	ds_read_u16 v216, v215 offset:8448
	v_mul_f32_e32 v220, 0x3fb8aa3b, v220
	v_mul_f32_e32 v217, v84, v147
	v_mul_f32_e32 v217, 0x3fb8aa3b, v217
	v_exp_f32_e32 v217, v217
	s_waitcnt lgkmcnt(0)
	v_lshlrev_b32_e32 v216, 16, v216
	v_mul_f32_e32 v218, v84, v148
	v_mul_f32_e32 v218, 0x3fb8aa3b, v218
	v_mul_f32_e32 v216, v217, v216
	ds_read_u16 v217, v205
	v_exp_f32_e32 v218, v218
	v_mul_f32_e32 v219, v84, v149
	v_mul_f32_e32 v219, 0x3fb8aa3b, v219
	v_exp_f32_e32 v219, v219
	s_waitcnt lgkmcnt(0)
	v_lshlrev_b32_e32 v217, 16, v217
	v_mul_f32_e32 v217, v218, v217
	ds_read_u16 v218, v205 offset:528
	v_exp_f32_e32 v220, v220
	v_mul_f32_e32 v221, v84, v151
	v_mul_f32_e32 v221, 0x3fb8aa3b, v221
	v_exp_f32_e32 v221, v221
	s_waitcnt lgkmcnt(0)
	v_lshlrev_b32_e32 v218, 16, v218
	v_mul_f32_e32 v218, v219, v218
	ds_read_u16 v219, v205 offset:1056
	v_mul_f32_e32 v222, v84, v152
	v_mul_f32_e32 v222, 0x3fb8aa3b, v222
	v_exp_f32_e32 v222, v222
	v_mul_f32_e32 v223, v84, v153
	s_waitcnt lgkmcnt(0)
	v_lshlrev_b32_e32 v219, 16, v219
	v_mul_f32_e32 v219, v220, v219
	ds_read_u16 v220, v205 offset:1584
	v_mul_f32_e32 v223, 0x3fb8aa3b, v223
	v_exp_f32_e32 v223, v223
	v_mul_f32_e32 v224, v84, v154
	v_mul_f32_e32 v224, 0x3fb8aa3b, v224
	s_waitcnt lgkmcnt(0)
	v_lshlrev_b32_e32 v220, 16, v220
	v_mul_f32_e32 v220, v221, v220
	ds_read_u16 v221, v205 offset:2112
	v_exp_f32_e32 v224, v224
	v_readlane_b32 s39, v254, 28
	s_waitcnt lgkmcnt(0)
	v_lshlrev_b32_e32 v221, 16, v221
	v_mul_f32_e32 v221, v222, v221
	ds_read_u16 v222, v205 offset:2640
	s_waitcnt lgkmcnt(0)
	v_lshlrev_b32_e32 v222, 16, v222
	v_mul_f32_e32 v222, v223, v222
	ds_read_u16 v223, v205 offset:3168
	v_cvt_pk_bf16_f32 v216, v216, v217
	v_cvt_pk_bf16_f32 v217, v218, v219
	v_cvt_pk_bf16_f32 v218, v220, v221
	v_mul_f32_e32 v220, v84, v158
	s_waitcnt lgkmcnt(0)
	v_lshlrev_b32_e32 v223, 16, v223
	v_mul_f32_e32 v223, v224, v223
	v_cvt_pk_bf16_f32 v219, v222, v223
	global_store_dwordx4 v[80:81], v[216:219], off offset:-1536
	ds_read_u16 v216, v215 offset:16896
	v_mul_f32_e32 v220, 0x3fb8aa3b, v220
	v_mul_f32_e32 v217, v84, v155
	v_mul_f32_e32 v217, 0x3fb8aa3b, v217
	v_exp_f32_e32 v217, v217
	s_waitcnt lgkmcnt(0)
	v_lshlrev_b32_e32 v216, 16, v216
	v_mul_f32_e32 v218, v84, v156
	v_mul_f32_e32 v218, 0x3fb8aa3b, v218
	v_mul_f32_e32 v216, v217, v216
	ds_read_u16 v217, v206
	v_exp_f32_e32 v218, v218
	v_mul_f32_e32 v219, v84, v157
	v_mul_f32_e32 v219, 0x3fb8aa3b, v219
	v_exp_f32_e32 v219, v219
	s_waitcnt lgkmcnt(0)
	v_lshlrev_b32_e32 v217, 16, v217
	v_mul_f32_e32 v217, v218, v217
	ds_read_u16 v218, v206 offset:528
	v_exp_f32_e32 v220, v220
	v_mul_f32_e32 v221, v84, v159
	v_mul_f32_e32 v221, 0x3fb8aa3b, v221
	v_exp_f32_e32 v221, v221
	s_waitcnt lgkmcnt(0)
	v_lshlrev_b32_e32 v218, 16, v218
	v_mul_f32_e32 v218, v219, v218
	ds_read_u16 v219, v206 offset:1056
	v_mul_f32_e32 v222, v84, v160
	v_mul_f32_e32 v222, 0x3fb8aa3b, v222
	v_exp_f32_e32 v222, v222
	v_mul_f32_e32 v223, v84, v161
	s_waitcnt lgkmcnt(0)
	v_lshlrev_b32_e32 v219, 16, v219
	v_mul_f32_e32 v219, v220, v219
	ds_read_u16 v220, v206 offset:1584
	v_mul_f32_e32 v223, 0x3fb8aa3b, v223
	v_exp_f32_e32 v223, v223
	v_mul_f32_e32 v224, v84, v162
	v_mul_f32_e32 v224, 0x3fb8aa3b, v224
	s_waitcnt lgkmcnt(0)
	v_lshlrev_b32_e32 v220, 16, v220
	v_mul_f32_e32 v220, v221, v220
	ds_read_u16 v221, v206 offset:2112
	v_exp_f32_e32 v224, v224
	s_waitcnt lgkmcnt(0)
	v_lshlrev_b32_e32 v221, 16, v221
	v_mul_f32_e32 v221, v222, v221
	ds_read_u16 v222, v206 offset:2640
	s_waitcnt lgkmcnt(0)
	v_lshlrev_b32_e32 v222, 16, v222
	v_mul_f32_e32 v222, v223, v222
	ds_read_u16 v223, v206 offset:3168
	v_cvt_pk_bf16_f32 v216, v216, v217
	v_cvt_pk_bf16_f32 v217, v218, v219
	v_cvt_pk_bf16_f32 v218, v220, v221
	v_mul_f32_e32 v220, v84, v166
	s_waitcnt lgkmcnt(0)
	v_lshlrev_b32_e32 v223, 16, v223
	v_mul_f32_e32 v223, v224, v223
	v_cvt_pk_bf16_f32 v219, v222, v223
	global_store_dwordx4 v[80:81], v[216:219], off offset:-1024
	ds_read_u16 v216, v215 offset:25344
	v_mul_f32_e32 v220, 0x3fb8aa3b, v220
	v_mul_f32_e32 v217, v84, v163
	v_mul_f32_e32 v217, 0x3fb8aa3b, v217
	v_exp_f32_e32 v217, v217
	s_waitcnt lgkmcnt(0)
	v_lshlrev_b32_e32 v216, 16, v216
	v_mul_f32_e32 v218, v84, v164
	v_mul_f32_e32 v218, 0x3fb8aa3b, v218
	v_mul_f32_e32 v216, v217, v216
	ds_read_u16 v217, v207
	v_exp_f32_e32 v218, v218
	v_mul_f32_e32 v219, v84, v165
	v_mul_f32_e32 v219, 0x3fb8aa3b, v219
	v_exp_f32_e32 v219, v219
	s_waitcnt lgkmcnt(0)
	v_lshlrev_b32_e32 v217, 16, v217
	v_mul_f32_e32 v217, v218, v217
	ds_read_u16 v218, v207 offset:528
	v_exp_f32_e32 v220, v220
	v_mul_f32_e32 v221, v84, v167
	v_mul_f32_e32 v221, 0x3fb8aa3b, v221
	v_exp_f32_e32 v221, v221
	s_waitcnt lgkmcnt(0)
	v_lshlrev_b32_e32 v218, 16, v218
	v_mul_f32_e32 v218, v219, v218
	ds_read_u16 v219, v207 offset:1056
	v_mul_f32_e32 v222, v84, v168
	v_mul_f32_e32 v222, 0x3fb8aa3b, v222
	v_exp_f32_e32 v222, v222
	v_mul_f32_e32 v223, v84, v169
	s_waitcnt lgkmcnt(0)
	v_lshlrev_b32_e32 v219, 16, v219
	v_mul_f32_e32 v219, v220, v219
	ds_read_u16 v220, v207 offset:1584
	v_mul_f32_e32 v223, 0x3fb8aa3b, v223
	v_exp_f32_e32 v223, v223
	v_mul_f32_e32 v224, v84, v170
	v_mul_f32_e32 v224, 0x3fb8aa3b, v224
	s_waitcnt lgkmcnt(0)
	v_lshlrev_b32_e32 v220, 16, v220
	v_mul_f32_e32 v220, v221, v220
	ds_read_u16 v221, v207 offset:2112
	v_exp_f32_e32 v224, v224
	s_waitcnt lgkmcnt(0)
	v_lshlrev_b32_e32 v221, 16, v221
	v_mul_f32_e32 v221, v222, v221
	ds_read_u16 v222, v207 offset:2640
	s_waitcnt lgkmcnt(0)
	v_lshlrev_b32_e32 v222, 16, v222
	v_mul_f32_e32 v222, v223, v222
	ds_read_u16 v223, v207 offset:3168
	v_cvt_pk_bf16_f32 v216, v216, v217
	v_cvt_pk_bf16_f32 v217, v218, v219
	v_cvt_pk_bf16_f32 v218, v220, v221
	v_mul_f32_e32 v220, v84, v174
	s_waitcnt lgkmcnt(0)
	v_lshlrev_b32_e32 v223, 16, v223
	v_mul_f32_e32 v223, v224, v223
	v_cvt_pk_bf16_f32 v219, v222, v223
	global_store_dwordx4 v[80:81], v[216:219], off offset:-512
	ds_read_u16 v216, v215 offset:33792
	v_mul_f32_e32 v220, 0x3fb8aa3b, v220
	v_mul_f32_e32 v217, v84, v171
	v_mul_f32_e32 v217, 0x3fb8aa3b, v217
	v_exp_f32_e32 v217, v217
	s_waitcnt lgkmcnt(0)
	v_lshlrev_b32_e32 v216, 16, v216
	v_mul_f32_e32 v218, v84, v172
	v_mul_f32_e32 v218, 0x3fb8aa3b, v218
	v_mul_f32_e32 v216, v217, v216
	ds_read_u16 v217, v208
	v_exp_f32_e32 v218, v218
	v_mul_f32_e32 v219, v84, v173
	v_mul_f32_e32 v219, 0x3fb8aa3b, v219
	v_exp_f32_e32 v219, v219
	s_waitcnt lgkmcnt(0)
	v_lshlrev_b32_e32 v217, 16, v217
	v_mul_f32_e32 v217, v218, v217
	ds_read_u16 v218, v208 offset:528
	v_exp_f32_e32 v220, v220
	v_mul_f32_e32 v221, v84, v175
	v_mul_f32_e32 v221, 0x3fb8aa3b, v221
	v_exp_f32_e32 v221, v221
	s_waitcnt lgkmcnt(0)
	v_lshlrev_b32_e32 v218, 16, v218
	v_mul_f32_e32 v218, v219, v218
	ds_read_u16 v219, v208 offset:1056
	v_mul_f32_e32 v222, v84, v176
	v_mul_f32_e32 v222, 0x3fb8aa3b, v222
	v_exp_f32_e32 v222, v222
	v_mul_f32_e32 v223, v84, v177
	s_waitcnt lgkmcnt(0)
	v_lshlrev_b32_e32 v219, 16, v219
	v_mul_f32_e32 v219, v220, v219
	ds_read_u16 v220, v208 offset:1584
	v_mul_f32_e32 v223, 0x3fb8aa3b, v223
	v_exp_f32_e32 v223, v223
	v_mul_f32_e32 v224, v84, v178
	v_mul_f32_e32 v224, 0x3fb8aa3b, v224
	s_waitcnt lgkmcnt(0)
	v_lshlrev_b32_e32 v220, 16, v220
	v_mul_f32_e32 v220, v221, v220
	ds_read_u16 v221, v208 offset:2112
	v_exp_f32_e32 v224, v224
	s_waitcnt lgkmcnt(0)
	v_lshlrev_b32_e32 v221, 16, v221
	v_mul_f32_e32 v221, v222, v221
	ds_read_u16 v222, v208 offset:2640
	s_waitcnt lgkmcnt(0)
	v_lshlrev_b32_e32 v222, 16, v222
	v_mul_f32_e32 v222, v223, v222
	ds_read_u16 v223, v208 offset:3168
	v_cvt_pk_bf16_f32 v216, v216, v217
	v_cvt_pk_bf16_f32 v217, v218, v219
	v_cvt_pk_bf16_f32 v218, v220, v221
	v_mul_f32_e32 v220, v84, v182
	s_waitcnt lgkmcnt(0)
	v_lshlrev_b32_e32 v223, 16, v223
	v_mul_f32_e32 v223, v224, v223
	v_cvt_pk_bf16_f32 v219, v222, v223
	global_store_dwordx4 v[80:81], v[216:219], off
	ds_read_u16 v216, v215 offset:42240
	v_mul_f32_e32 v220, 0x3fb8aa3b, v220
	v_mul_f32_e32 v217, v84, v179
	v_mul_f32_e32 v217, 0x3fb8aa3b, v217
	v_exp_f32_e32 v217, v217
	s_waitcnt lgkmcnt(0)
	v_lshlrev_b32_e32 v216, 16, v216
	v_mul_f32_e32 v218, v84, v180
	v_mul_f32_e32 v218, 0x3fb8aa3b, v218
	v_mul_f32_e32 v216, v217, v216
	ds_read_u16 v217, v209
	v_exp_f32_e32 v218, v218
	v_mul_f32_e32 v219, v84, v181
	v_mul_f32_e32 v219, 0x3fb8aa3b, v219
	v_exp_f32_e32 v219, v219
	s_waitcnt lgkmcnt(0)
	v_lshlrev_b32_e32 v217, 16, v217
	v_mul_f32_e32 v217, v218, v217
	ds_read_u16 v218, v209 offset:528
	v_exp_f32_e32 v220, v220
	v_mul_f32_e32 v221, v84, v183
	v_mul_f32_e32 v221, 0x3fb8aa3b, v221
	v_exp_f32_e32 v221, v221
	s_waitcnt lgkmcnt(0)
	v_lshlrev_b32_e32 v218, 16, v218
	v_mul_f32_e32 v218, v219, v218
	ds_read_u16 v219, v209 offset:1056
	v_mul_f32_e32 v222, v84, v184
	v_mul_f32_e32 v222, 0x3fb8aa3b, v222
	v_exp_f32_e32 v222, v222
	v_mul_f32_e32 v223, v84, v185
	s_waitcnt lgkmcnt(0)
	v_lshlrev_b32_e32 v219, 16, v219
	v_mul_f32_e32 v219, v220, v219
	ds_read_u16 v220, v209 offset:1584
	v_mul_f32_e32 v223, 0x3fb8aa3b, v223
	v_exp_f32_e32 v223, v223
	v_mul_f32_e32 v224, v84, v186
	v_mul_f32_e32 v224, 0x3fb8aa3b, v224
	s_waitcnt lgkmcnt(0)
	v_lshlrev_b32_e32 v220, 16, v220
	v_mul_f32_e32 v220, v221, v220
	ds_read_u16 v221, v209 offset:2112
	v_exp_f32_e32 v224, v224
	s_waitcnt lgkmcnt(0)
	v_lshlrev_b32_e32 v221, 16, v221
	v_mul_f32_e32 v221, v222, v221
	ds_read_u16 v222, v209 offset:2640
	s_waitcnt lgkmcnt(0)
	v_lshlrev_b32_e32 v222, 16, v222
	v_mul_f32_e32 v222, v223, v222
	ds_read_u16 v223, v209 offset:3168
	v_cvt_pk_bf16_f32 v216, v216, v217
	v_cvt_pk_bf16_f32 v217, v218, v219
	v_cvt_pk_bf16_f32 v218, v220, v221
	v_mul_f32_e32 v220, v84, v191
	s_waitcnt lgkmcnt(0)
	v_lshlrev_b32_e32 v223, 16, v223
	v_mul_f32_e32 v223, v224, v223
	v_cvt_pk_bf16_f32 v219, v222, v223
	global_store_dwordx4 v[80:81], v[216:219], off offset:512
	ds_read_u16 v215, v215 offset:50688
	v_mul_f32_e32 v220, 0x3fb8aa3b, v220
	v_mul_f32_e32 v216, v84, v187
	v_mul_f32_e32 v216, 0x3fb8aa3b, v216
	v_exp_f32_e32 v216, v216
	s_waitcnt lgkmcnt(0)
	v_lshlrev_b32_e32 v215, 16, v215
	v_mul_f32_e32 v217, v84, v188
	v_mul_f32_e32 v217, 0x3fb8aa3b, v217
	v_mul_f32_e32 v215, v216, v215
	ds_read_u16 v216, v210
	v_exp_f32_e32 v217, v217
	v_mul_f32_e32 v218, v84, v189
	v_mul_f32_e32 v218, 0x3fb8aa3b, v218
	v_exp_f32_e32 v218, v218
	s_waitcnt lgkmcnt(0)
	v_lshlrev_b32_e32 v216, 16, v216
	v_mul_f32_e32 v216, v217, v216
	ds_read_u16 v217, v210 offset:528
	v_mul_f32_e32 v219, v84, v190
	v_mul_f32_e32 v219, 0x3fb8aa3b, v219
	v_exp_f32_e32 v219, v219
	v_exp_f32_e32 v220, v220
	s_waitcnt lgkmcnt(0)
	v_lshlrev_b32_e32 v217, 16, v217
	v_mul_f32_e32 v217, v218, v217
	ds_read_u16 v218, v210 offset:1056
	v_mul_f32_e32 v221, v84, v192
	v_mul_f32_e32 v221, 0x3fb8aa3b, v221
	v_exp_f32_e32 v221, v221
	v_mul_f32_e32 v222, v84, v193
	s_waitcnt lgkmcnt(0)
	v_lshlrev_b32_e32 v218, 16, v218
	v_mul_f32_e32 v218, v219, v218
	ds_read_u16 v219, v210 offset:1584
	v_mul_f32_e32 v222, 0x3fb8aa3b, v222
	v_exp_f32_e32 v222, v222
	v_mul_f32_e32 v223, v84, v194
	v_mul_f32_e32 v223, 0x3fb8aa3b, v223
	s_waitcnt lgkmcnt(0)
	v_lshlrev_b32_e32 v219, 16, v219
	v_mul_f32_e32 v219, v220, v219
	ds_read_u16 v220, v210 offset:2112
	v_exp_f32_e32 v223, v223
	s_waitcnt lgkmcnt(0)
	v_lshlrev_b32_e32 v220, 16, v220
	v_mul_f32_e32 v220, v221, v220
	ds_read_u16 v221, v210 offset:2640
	s_waitcnt lgkmcnt(0)
	v_lshlrev_b32_e32 v221, 16, v221
	v_mul_f32_e32 v221, v222, v221
	ds_read_u16 v222, v210 offset:3168
	v_cvt_pk_bf16_f32 v216, v215, v216
	v_cvt_pk_bf16_f32 v217, v217, v218
	v_cvt_pk_bf16_f32 v218, v219, v220
	v_mul_f32_e32 v220, v84, v201
	s_waitcnt lgkmcnt(0)
	v_lshlrev_b32_e32 v222, 16, v222
	v_mul_f32_e32 v222, v223, v222
	v_cvt_pk_bf16_f32 v219, v221, v222
	global_store_dwordx4 v[80:81], v[216:219], off offset:1024
	ds_read_u16 v215, v211
	v_mul_f32_e32 v220, 0x3fb8aa3b, v220
	v_mul_f32_e32 v216, v84, v195
	v_mul_f32_e32 v216, 0x3fb8aa3b, v216
	v_exp_f32_e32 v216, v216
	s_waitcnt lgkmcnt(0)
	v_lshlrev_b32_e32 v215, 16, v215
	v_mul_f32_e32 v217, v84, v196
	v_mul_f32_e32 v217, 0x3fb8aa3b, v217
	v_mul_f32_e32 v215, v216, v215
	ds_read_u16 v216, v212
	v_exp_f32_e32 v217, v217
	v_mul_f32_e32 v218, v84, v197
	v_mul_f32_e32 v218, 0x3fb8aa3b, v218
	v_exp_f32_e32 v218, v218
	s_waitcnt lgkmcnt(0)
	v_lshlrev_b32_e32 v216, 16, v216
	v_mul_f32_e32 v216, v217, v216
	ds_read_u16 v217, v212 offset:528
	v_mul_f32_e32 v219, v84, v200
	v_mul_f32_e32 v219, 0x3fb8aa3b, v219
	v_exp_f32_e32 v219, v219
	v_exp_f32_e32 v220, v220
	s_waitcnt lgkmcnt(0)
	v_lshlrev_b32_e32 v217, 16, v217
	v_mul_f32_e32 v217, v218, v217
	ds_read_u16 v218, v212 offset:1056
	v_mul_f32_e32 v221, v84, v202
	v_mul_f32_e32 v221, 0x3fb8aa3b, v221
	v_exp_f32_e32 v221, v221
	v_mul_f32_e32 v222, v84, v203
	s_waitcnt lgkmcnt(0)
	v_lshlrev_b32_e32 v218, 16, v218
	v_mul_f32_e32 v218, v219, v218
	ds_read_u16 v219, v212 offset:1584
	v_mul_f32_e32 v222, 0x3fb8aa3b, v222
	v_exp_f32_e32 v222, v222
	v_mul_f32_e32 v84, v84, v204
	v_mul_f32_e32 v84, 0x3fb8aa3b, v84
	s_waitcnt lgkmcnt(0)
	v_lshlrev_b32_e32 v219, 16, v219
	v_mul_f32_e32 v219, v220, v219
	ds_read_u16 v220, v212 offset:2112
	v_exp_f32_e32 v84, v84
	s_waitcnt lgkmcnt(0)
	v_lshlrev_b32_e32 v220, 16, v220
	v_mul_f32_e32 v220, v221, v220
	ds_read_u16 v221, v212 offset:2640
	s_waitcnt lgkmcnt(0)
	v_lshlrev_b32_e32 v221, 16, v221
	v_mul_f32_e32 v221, v222, v221
	ds_read_u16 v222, v212 offset:3168
	v_cvt_pk_bf16_f32 v216, v215, v216
	v_cvt_pk_bf16_f32 v217, v217, v218
	v_cvt_pk_bf16_f32 v218, v219, v220
	s_waitcnt lgkmcnt(0)
	v_lshlrev_b32_e32 v222, 16, v222
	v_mul_f32_e32 v84, v84, v222
	v_cvt_pk_bf16_f32 v219, v221, v84
	global_store_dwordx4 v[80:81], v[216:219], off offset:1536
	v_lshl_add_u64 v[80:81], v[80:81], 0, s[14:15]
	s_cbranch_vccz .LBB0_1259

.LBB0_1245:
	s_or_b64 exec, exec, vcc
	v_cvt_pk_bf16_f32 v216, v216, v217
	v_cvt_pk_bf16_f32 v217, v218, v219
	global_store_dwordx2 v[82:83], v[216:217], off offset:-2048
	v_mov_b32_e32 v216, 0
	v_mov_b32_e32 v217, 0
	v_mov_b32_e32 v218, 0
	s_and_saveexec_b64 vcc, s[16:17]
	s_cbranch_execz .LBB0_1247
	ds_read_b128 v[216:219], v106 offset:8448
	ds_read_b128 v[220:223], v87
	v_mul_f32_e32 v215, v84, v111
	v_mul_f32_e32 v215, 0x3fb8aa3b, v215
	v_readlane_b32 s38, v255, 3
	v_readlane_b32 s39, v255, 4
	s_waitcnt lgkmcnt(0)
	v_mfma_f32_16x16x32_bf16 v[216:219], v[216:219], v[220:223], 0
	ds_read_b128 v[220:223], v106 offset:8512
	ds_read_b128 v[224:227], v87 offset:64
	s_waitcnt lgkmcnt(0)
	v_mfma_f32_16x16x32_bf16 v[216:219], v[220:223], v[224:227], v[216:219]
	ds_read_b128 v[220:223], v106 offset:8576
	ds_read_b128 v[224:227], v87 offset:128
	s_waitcnt lgkmcnt(0)
	v_mfma_f32_16x16x32_bf16 v[216:219], v[220:223], v[224:227], v[216:219]
	ds_read_b128 v[220:223], v106 offset:8640
	ds_read_b128 v[224:227], v87 offset:192
	s_waitcnt lgkmcnt(0)
	v_mfma_f32_16x16x32_bf16 v[216:219], v[220:223], v[224:227], v[216:219]
	ds_read_b128 v[220:223], v106 offset:8704
	ds_read_b128 v[224:227], v87 offset:256
	s_waitcnt lgkmcnt(0)
	v_mfma_f32_16x16x32_bf16 v[216:219], v[220:223], v[224:227], v[216:219]
	ds_read_b128 v[220:223], v106 offset:8768
	ds_read_b128 v[224:227], v87 offset:320
	s_waitcnt lgkmcnt(0)
	v_mfma_f32_16x16x32_bf16 v[216:219], v[220:223], v[224:227], v[216:219]
	ds_read_b128 v[220:223], v106 offset:8832
	ds_read_b128 v[224:227], v87 offset:384
	s_waitcnt lgkmcnt(0)
	v_mfma_f32_16x16x32_bf16 v[216:219], v[220:223], v[224:227], v[216:219]
	ds_read_b128 v[220:223], v106 offset:8896
	ds_read_b128 v[224:227], v87 offset:448
	s_waitcnt lgkmcnt(0)
	v_mfma_f32_16x16x32_bf16 v[216:219], v[220:223], v[224:227], v[216:219]
	v_exp_f32_e32 v220, v215
	v_mul_f32_e32 v215, v84, v112
	v_mul_f32_e32 v215, 0x3fb8aa3b, v215
	v_exp_f32_e32 v221, v215
	v_mul_f32_e32 v215, v84, v113
	v_mul_f32_e32 v215, 0x3fb8aa3b, v215
	v_exp_f32_e32 v222, v215
	v_mul_f32_e32 v215, v84, v114
	v_mul_f32_e32 v215, 0x3fb8aa3b, v215
	v_exp_f32_e32 v223, v215
	v_pk_mul_f32 v[216:217], v[220:221], v[216:217]
	v_pk_mul_f32 v[218:219], v[222:223], v[218:219]
	v_cndmask_b32_e64 v215, v216, 0, s[38:39]
	v_readlane_b32 s38, v255, 1
	v_readlane_b32 s39, v255, 2
	s_nop 1
	v_cndmask_b32_e64 v216, v217, 0, s[38:39]
	v_readlane_b32 s38, v254, 63
	v_readlane_b32 s39, v255, 0
	s_nop 1
	v_cndmask_b32_e64 v217, v218, 0, s[38:39]
	v_readlane_b32 s38, v254, 51
	v_readlane_b32 s39, v254, 52
	s_nop 1
	v_cndmask_b32_e64 v218, v219, 0, s[38:39]
.LBB0_1247:
	s_or_b64 exec, exec, vcc
	v_cvt_pk_bf16_f32 v216, v215, v216
	v_cvt_pk_bf16_f32 v217, v217, v218
	global_store_dwordx2 v[82:83], v[216:217], off offset:-1536
	v_mov_b32_e32 v215, 0
	v_mov_b32_e32 v216, 0
	v_mov_b32_e32 v217, 0
	v_mov_b32_e32 v218, 0
	v_mov_b32_e32 v219, 0
	s_and_saveexec_b64 vcc, s[18:19]
	s_cbranch_execz .LBB0_1249
	ds_read_b128 v[216:219], v106 offset:16896
	ds_read_b128 v[220:223], v87
	v_readlane_b32 s38, v255, 5
	v_readlane_b32 s39, v255, 6
	s_waitcnt lgkmcnt(0)
	v_mfma_f32_16x16x32_bf16 v[216:219], v[216:219], v[220:223], 0
	ds_read_b128 v[220:223], v106 offset:16960
	ds_read_b128 v[224:227], v87 offset:64
	s_waitcnt lgkmcnt(0)
	v_mfma_f32_16x16x32_bf16 v[216:219], v[220:223], v[224:227], v[216:219]
	ds_read_b128 v[220:223], v106 offset:17024
	ds_read_b128 v[224:227], v87 offset:128
	s_waitcnt lgkmcnt(0)
	v_mfma_f32_16x16x32_bf16 v[216:219], v[220:223], v[224:227], v[216:219]
	ds_read_b128 v[220:223], v106 offset:17088
	ds_read_b128 v[224:227], v87 offset:192
	s_waitcnt lgkmcnt(0)
	v_mfma_f32_16x16x32_bf16 v[216:219], v[220:223], v[224:227], v[216:219]
	ds_read_b128 v[220:223], v106 offset:17152
	ds_read_b128 v[224:227], v87 offset:256
	s_waitcnt lgkmcnt(0)
	v_mfma_f32_16x16x32_bf16 v[216:219], v[220:223], v[224:227], v[216:219]
	ds_read_b128 v[220:223], v106 offset:17216
	ds_read_b128 v[224:227], v87 offset:320
	s_waitcnt lgkmcnt(0)
	v_mfma_f32_16x16x32_bf16 v[216:219], v[220:223], v[224:227], v[216:219]
	ds_read_b128 v[220:223], v106 offset:17280
	ds_read_b128 v[224:227], v87 offset:384
	s_waitcnt lgkmcnt(0)
	v_mfma_f32_16x16x32_bf16 v[216:219], v[220:223], v[224:227], v[216:219]
	ds_read_b128 v[220:223], v106 offset:17344
	ds_read_b128 v[224:227], v87 offset:448
	s_waitcnt lgkmcnt(0)
	v_mfma_f32_16x16x32_bf16 v[216:219], v[220:223], v[224:227], v[216:219]
	v_mul_f32_e32 v220, v84, v115
	v_mul_f32_e32 v221, v84, v116
	v_mul_f32_e32 v222, v84, v117
	v_mul_f32_e32 v223, v84, v118
	v_mul_f32_e32 v220, 0x3fb8aa3b, v220
	v_mul_f32_e32 v221, 0x3fb8aa3b, v221
	v_mul_f32_e32 v222, 0x3fb8aa3b, v222
	v_mul_f32_e32 v223, 0x3fb8aa3b, v223
	v_exp_f32_e32 v220, v220
	v_exp_f32_e32 v221, v221
	v_exp_f32_e32 v222, v222
	v_exp_f32_e32 v223, v223
	v_pk_mul_f32 v[216:217], v[220:221], v[216:217]
	s_nop 0
	v_cndmask_b32_e64 v216, v216, 0, s[46:47]
	v_pk_mul_f32 v[218:219], v[222:223], v[218:219]
	v_cndmask_b32_e64 v217, v217, 0, s[42:43]
	v_cndmask_b32_e64 v218, v218, 0, s[40:41]
	v_cndmask_b32_e64 v219, v219, 0, s[38:39]
.LBB0_1249:
	s_or_b64 exec, exec, vcc
	v_cvt_pk_bf16_f32 v216, v216, v217
	v_cvt_pk_bf16_f32 v217, v218, v219
	global_store_dwordx2 v[82:83], v[216:217], off offset:-1024
	v_mov_b32_e32 v216, 0
	v_mov_b32_e32 v217, 0
	v_mov_b32_e32 v218, 0
	s_and_saveexec_b64 vcc, s[20:21]
	s_cbranch_execz .LBB0_1251
	ds_read_b128 v[216:219], v106 offset:25344
	ds_read_b128 v[220:223], v87
	v_mul_f32_e32 v215, v84, v119
	v_mul_f32_e32 v215, 0x3fb8aa3b, v215
	s_waitcnt lgkmcnt(0)
	v_mfma_f32_16x16x32_bf16 v[216:219], v[216:219], v[220:223], 0
	ds_read_b128 v[220:223], v106 offset:25408
	ds_read_b128 v[224:227], v87 offset:64
	s_waitcnt lgkmcnt(0)
	v_mfma_f32_16x16x32_bf16 v[216:219], v[220:223], v[224:227], v[216:219]
	ds_read_b128 v[220:223], v106 offset:25472
	ds_read_b128 v[224:227], v87 offset:128
	s_waitcnt lgkmcnt(0)
	v_mfma_f32_16x16x32_bf16 v[216:219], v[220:223], v[224:227], v[216:219]
	ds_read_b128 v[220:223], v106 offset:25536
	ds_read_b128 v[224:227], v87 offset:192
	s_waitcnt lgkmcnt(0)
	v_mfma_f32_16x16x32_bf16 v[216:219], v[220:223], v[224:227], v[216:219]
	ds_read_b128 v[220:223], v106 offset:25600
	ds_read_b128 v[224:227], v87 offset:256
	s_waitcnt lgkmcnt(0)
	v_mfma_f32_16x16x32_bf16 v[216:219], v[220:223], v[224:227], v[216:219]
	ds_read_b128 v[220:223], v106 offset:25664
	ds_read_b128 v[224:227], v87 offset:320
	s_waitcnt lgkmcnt(0)
	v_mfma_f32_16x16x32_bf16 v[216:219], v[220:223], v[224:227], v[216:219]
	ds_read_b128 v[220:223], v106 offset:25728
	ds_read_b128 v[224:227], v87 offset:384
	s_waitcnt lgkmcnt(0)
	v_mfma_f32_16x16x32_bf16 v[216:219], v[220:223], v[224:227], v[216:219]
	ds_read_b128 v[220:223], v106 offset:25792
	ds_read_b128 v[224:227], v87 offset:448
	s_waitcnt lgkmcnt(0)
	v_mfma_f32_16x16x32_bf16 v[216:219], v[220:223], v[224:227], v[216:219]
	v_exp_f32_e32 v220, v215
	v_mul_f32_e32 v215, v84, v120
	v_mul_f32_e32 v215, 0x3fb8aa3b, v215
	v_exp_f32_e32 v221, v215
	v_mul_f32_e32 v215, v84, v121
	v_mul_f32_e32 v215, 0x3fb8aa3b, v215
	v_exp_f32_e32 v222, v215
	v_mul_f32_e32 v215, v84, v122
	v_mul_f32_e32 v215, 0x3fb8aa3b, v215
	v_exp_f32_e32 v223, v215
	v_pk_mul_f32 v[216:217], v[220:221], v[216:217]
	v_pk_mul_f32 v[218:219], v[222:223], v[218:219]
	v_cndmask_b32_e64 v215, v216, 0, s[54:55]
	v_cndmask_b32_e64 v216, v217, 0, s[52:53]
	v_cndmask_b32_e64 v217, v218, 0, s[50:51]
	v_cndmask_b32_e64 v218, v219, 0, s[48:49]
.LBB0_1251:
	s_or_b64 exec, exec, vcc
	v_cvt_pk_bf16_f32 v216, v215, v216
	v_cvt_pk_bf16_f32 v217, v217, v218
	global_store_dwordx2 v[82:83], v[216:217], off offset:-512
	v_mov_b32_e32 v215, 0
	v_mov_b32_e32 v216, 0
	v_mov_b32_e32 v217, 0
	v_mov_b32_e32 v218, 0
	v_mov_b32_e32 v219, 0
	s_and_saveexec_b64 vcc, s[22:23]
	s_cbranch_execz .LBB0_1253
	ds_read_b128 v[216:219], v106 offset:33792
	ds_read_b128 v[220:223], v87
	s_waitcnt lgkmcnt(0)
	v_mfma_f32_16x16x32_bf16 v[216:219], v[216:219], v[220:223], 0
	ds_read_b128 v[220:223], v106 offset:33856
	ds_read_b128 v[224:227], v87 offset:64
	s_waitcnt lgkmcnt(0)
	v_mfma_f32_16x16x32_bf16 v[216:219], v[220:223], v[224:227], v[216:219]
	ds_read_b128 v[220:223], v106 offset:33920
	ds_read_b128 v[224:227], v87 offset:128
	s_waitcnt lgkmcnt(0)
	v_mfma_f32_16x16x32_bf16 v[216:219], v[220:223], v[224:227], v[216:219]
	ds_read_b128 v[220:223], v106 offset:33984
	ds_read_b128 v[224:227], v87 offset:192
	s_waitcnt lgkmcnt(0)
	v_mfma_f32_16x16x32_bf16 v[216:219], v[220:223], v[224:227], v[216:219]
	ds_read_b128 v[220:223], v106 offset:34048
	ds_read_b128 v[224:227], v87 offset:256
	s_waitcnt lgkmcnt(0)
	v_mfma_f32_16x16x32_bf16 v[216:219], v[220:223], v[224:227], v[216:219]
	ds_read_b128 v[220:223], v106 offset:34112
	ds_read_b128 v[224:227], v87 offset:320
	s_waitcnt lgkmcnt(0)
	v_mfma_f32_16x16x32_bf16 v[216:219], v[220:223], v[224:227], v[216:219]
	ds_read_b128 v[220:223], v106 offset:34176
	ds_read_b128 v[224:227], v87 offset:384
	s_waitcnt lgkmcnt(0)
	v_mfma_f32_16x16x32_bf16 v[216:219], v[220:223], v[224:227], v[216:219]
	ds_read_b128 v[220:223], v106 offset:34240
	ds_read_b128 v[224:227], v87 offset:448
	s_waitcnt lgkmcnt(0)
	v_mfma_f32_16x16x32_bf16 v[216:219], v[220:223], v[224:227], v[216:219]
	v_mul_f32_e32 v220, v84, v123
	v_mul_f32_e32 v221, v84, v124
	v_mul_f32_e32 v222, v84, v125
	v_mul_f32_e32 v223, v84, v126
	v_mul_f32_e32 v220, 0x3fb8aa3b, v220
	v_mul_f32_e32 v221, 0x3fb8aa3b, v221
	v_mul_f32_e32 v222, 0x3fb8aa3b, v222
	v_mul_f32_e32 v223, 0x3fb8aa3b, v223
	v_exp_f32_e32 v220, v220
	v_exp_f32_e32 v221, v221
	v_exp_f32_e32 v222, v222
	v_exp_f32_e32 v223, v223
	v_pk_mul_f32 v[216:217], v[220:221], v[216:217]
	s_nop 0
	v_cndmask_b32_e64 v216, v216, 0, s[62:63]
	v_pk_mul_f32 v[218:219], v[222:223], v[218:219]
	v_cndmask_b32_e64 v217, v217, 0, s[60:61]
	v_cndmask_b32_e64 v218, v218, 0, s[58:59]
	v_cndmask_b32_e64 v219, v219, 0, s[56:57]

.LBB0_1255:
	s_or_b64 exec, exec, vcc
	v_cvt_pk_bf16_f32 v216, v215, v216
	v_cvt_pk_bf16_f32 v217, v217, v218
	global_store_dwordx2 v[82:83], v[216:217], off offset:512
	v_mov_b32_e32 v215, 0
	v_mov_b32_e32 v216, 0
	v_mov_b32_e32 v217, 0
	v_mov_b32_e32 v218, 0
	v_mov_b32_e32 v219, 0
	s_and_saveexec_b64 vcc, s[26:27]
	s_cbranch_execz .LBB0_1257
	ds_read_b128 v[216:219], v106 offset:50688
	ds_read_b128 v[220:223], v87
	s_waitcnt lgkmcnt(0)
	v_mfma_f32_16x16x32_bf16 v[216:219], v[216:219], v[220:223], 0
	ds_read_b128 v[220:223], v106 offset:50752
	ds_read_b128 v[224:227], v87 offset:64
	s_waitcnt lgkmcnt(0)
	v_mfma_f32_16x16x32_bf16 v[216:219], v[220:223], v[224:227], v[216:219]
	ds_read_b128 v[220:223], v106 offset:50816
	ds_read_b128 v[224:227], v87 offset:128
	s_waitcnt lgkmcnt(0)
	v_mfma_f32_16x16x32_bf16 v[216:219], v[220:223], v[224:227], v[216:219]
	ds_read_b128 v[220:223], v106 offset:50880
	ds_read_b128 v[224:227], v87 offset:192
	s_waitcnt lgkmcnt(0)
	v_mfma_f32_16x16x32_bf16 v[216:219], v[220:223], v[224:227], v[216:219]
	ds_read_b128 v[220:223], v106 offset:50944
	ds_read_b128 v[224:227], v87 offset:256
	s_waitcnt lgkmcnt(0)
	v_mfma_f32_16x16x32_bf16 v[216:219], v[220:223], v[224:227], v[216:219]
	ds_read_b128 v[220:223], v106 offset:51008
	ds_read_b128 v[224:227], v87 offset:320
	s_waitcnt lgkmcnt(0)
	v_mfma_f32_16x16x32_bf16 v[216:219], v[220:223], v[224:227], v[216:219]
	ds_read_b128 v[220:223], v106 offset:51072
	ds_read_b128 v[224:227], v87 offset:384
	s_waitcnt lgkmcnt(0)
	v_mfma_f32_16x16x32_bf16 v[216:219], v[220:223], v[224:227], v[216:219]
	ds_read_b128 v[220:223], v106 offset:51136
	ds_read_b128 v[224:227], v87 offset:448
	s_waitcnt lgkmcnt(0)
	v_mfma_f32_16x16x32_bf16 v[216:219], v[220:223], v[224:227], v[216:219]
	v_mul_f32_e32 v220, v84, v131
	v_mul_f32_e32 v221, v84, v132
	v_mul_f32_e32 v222, v84, v133
	v_mul_f32_e32 v223, v84, v134
	v_mul_f32_e32 v220, 0x3fb8aa3b, v220
	v_mul_f32_e32 v221, 0x3fb8aa3b, v221
	v_mul_f32_e32 v222, 0x3fb8aa3b, v222
	v_mul_f32_e32 v223, 0x3fb8aa3b, v223
	v_exp_f32_e32 v220, v220
	v_exp_f32_e32 v221, v221
	v_exp_f32_e32 v222, v222
	v_exp_f32_e32 v223, v223
	v_pk_mul_f32 v[216:217], v[220:221], v[216:217]
	s_nop 0
	v_cndmask_b32_e64 v216, v216, 0, s[78:79]
	v_pk_mul_f32 v[218:219], v[222:223], v[218:219]
	v_cndmask_b32_e64 v217, v217, 0, s[76:77]
	v_cndmask_b32_e64 v218, v218, 0, s[74:75]
	v_cndmask_b32_e64 v219, v219, 0, s[72:73]
.LBB0_1257:
	s_or_b64 exec, exec, vcc
	v_cvt_pk_bf16_f32 v216, v216, v217
	v_cvt_pk_bf16_f32 v217, v218, v219
	global_store_dwordx2 v[82:83], v[216:217], off offset:1024
	v_mov_b32_e32 v216, 0
	v_mov_b32_e32 v217, 0
	v_mov_b32_e32 v218, 0
	s_and_saveexec_b64 vcc, s[28:29]
	s_cbranch_execz .LBB0_1235
	ds_read_b128 v[216:219], v106 offset:59136
	ds_read_b128 v[220:223], v87
	v_mul_f32_e32 v215, v84, v135
	v_mul_f32_e32 v215, 0x3fb8aa3b, v215
	s_waitcnt lgkmcnt(0)
	v_mfma_f32_16x16x32_bf16 v[216:219], v[216:219], v[220:223], 0
	ds_read_b128 v[220:223], v106 offset:59200
	ds_read_b128 v[224:227], v87 offset:64
	s_waitcnt lgkmcnt(0)
	v_mfma_f32_16x16x32_bf16 v[216:219], v[220:223], v[224:227], v[216:219]
	ds_read_b128 v[220:223], v106 offset:59264
	ds_read_b128 v[224:227], v87 offset:128
	s_waitcnt lgkmcnt(0)
	v_mfma_f32_16x16x32_bf16 v[216:219], v[220:223], v[224:227], v[216:219]
	ds_read_b128 v[220:223], v106 offset:59328
	ds_read_b128 v[224:227], v87 offset:192
	s_waitcnt lgkmcnt(0)
	v_mfma_f32_16x16x32_bf16 v[216:219], v[220:223], v[224:227], v[216:219]
	ds_read_b128 v[220:223], v106 offset:59392
	ds_read_b128 v[224:227], v87 offset:256
	s_waitcnt lgkmcnt(0)
	v_mfma_f32_16x16x32_bf16 v[216:219], v[220:223], v[224:227], v[216:219]
	ds_read_b128 v[220:223], v106 offset:59456
	ds_read_b128 v[224:227], v87 offset:320
	s_waitcnt lgkmcnt(0)
	v_mfma_f32_16x16x32_bf16 v[216:219], v[220:223], v[224:227], v[216:219]
	ds_read_b128 v[220:223], v106 offset:59520
	ds_read_b128 v[224:227], v87 offset:384
	s_waitcnt lgkmcnt(0)
	v_mfma_f32_16x16x32_bf16 v[216:219], v[220:223], v[224:227], v[216:219]
	ds_read_b128 v[220:223], v106 offset:59584
	ds_read_b128 v[224:227], v87 offset:448
	s_waitcnt lgkmcnt(0)
	v_mfma_f32_16x16x32_bf16 v[216:219], v[220:223], v[224:227], v[216:219]
	v_exp_f32_e32 v220, v215
	v_mul_f32_e32 v215, v84, v136
	v_mul_f32_e32 v215, 0x3fb8aa3b, v215
	v_exp_f32_e32 v221, v215
	v_mul_f32_e32 v215, v84, v137
	v_mul_f32_e32 v215, 0x3fb8aa3b, v215
	v_exp_f32_e32 v222, v215
	v_mul_f32_e32 v215, v84, v138
	v_mul_f32_e32 v215, 0x3fb8aa3b, v215
	v_exp_f32_e32 v223, v215
	v_pk_mul_f32 v[216:217], v[220:221], v[216:217]
	v_pk_mul_f32 v[218:219], v[222:223], v[218:219]
	v_cndmask_b32_e64 v215, v216, 0, s[86:87]
	v_cndmask_b32_e64 v216, v217, 0, s[84:85]
	v_cndmask_b32_e64 v217, v218, 0, s[82:83]
	v_cndmask_b32_e64 v218, v219, 0, s[80:81]
	s_branch .LBB0_1235

.LBB0_1313:
	s_or_b64 exec, exec, s[0:1]
	s_add_u32 s6, s94, 0x2a402800
	s_addc_u32 s7, s95, 0
	s_cmpk_gt_u32 s2, 0x7f
	s_waitcnt lgkmcnt(0)
	s_barrier
	s_cbranch_scc1 .LBB0_1326
	s_and_b32 s76, s2, 7
	s_lshr_b32 s77, s2, 3
	s_lshr_b32 s78, s77, 3
	s_lshl_b32 s72, s76, 1
	s_add_u32 s72, s72, s78
	s_and_b32 s73, s77, 7
	s_lshr_b32 s74, s72, 2
	s_and_b32 s75, s72, 3
	s_mov_b32 s82, 0xbd020aec
	s_cmp_eq_u32 s75, 1
	s_cselect_b32 s82, 0xbc8102b3, s82
	s_cmp_eq_u32 s75, 2
	s_cselect_b32 s82, 0xbc0080ac, s82
	s_cmp_eq_u32 s75, 3
	s_cselect_b32 s82, 0xbb80402b, s82
	v_lshrrev_b32_e32 v210, 6, v198
	v_and_b32_e32 v211, 15, v198
	v_bfe_u32 v212, v198, 4, 2
	v_readfirstlane_b32 s71, v210
	v_lshl_or_b32 v213, v210, 4, v211
	v_add_u32_e32 v213, 1, v213
	v_cvt_f32_i32_e32 v213, v213
	v_mul_f32_e32 v213, s82, v213
	v_mul_f32_e32 v213, 0x3fb8aa3b, v213
	v_exp_f32_e32 v202, v213
	v_mov_b32_e32 v213, 0x43000000
	v_mul_f32_e32 v213, s82, v213
	v_mul_f32_e32 v213, 0x3fb8aa3b, v213
	v_exp_f32_e32 v204, v213
	s_nop 1
	v_mov_b32_e32 v203, v202
	v_mov_b32_e32 v205, v204
	v_lshlrev_b32_e32 v192, 4, v211
	v_lshl_add_u32 v192, v212, 8, v192
	v_lshlrev_b32_e32 v193, 11, v211
	v_lshl_add_u32 v193, v212, 4, v193
	v_lshlrev_b32_e32 v195, 12, v211
	v_lshl_add_u32 v195, v212, 3, v195
	v_lshrrev_b32_e32 v213, 3, v198
	v_and_b32_e32 v194, 7, v198
	v_lshlrev_b32_e32 v194, 5, v194
	v_mul_u32_u24_e32 v201, 272, v213
	v_add_u32_e32 v201, v201, v194
	v_lshl_add_u32 v194, v213, 13, v194
	v_add_u32_e32 v201, 67584, v201
	v_mul_u32_u24_e32 v196, 528, v211
	v_lshl_add_u32 v200, v212, 3, v196
	v_lshl_add_u32 v200, v210, 6, v200
	v_add_u32_e32 v200, 33792, v200
	v_lshl_add_u32 v196, v212, 4, v196
	v_mul_u32_u24_e32 v197, 272, v211
	v_lshl_add_u32 v197, v212, 4, v197
	v_add_u32_e32 v197, 67584, v197
	v_lshlrev_b32_e32 v206, 13, v212
	v_lshl_add_u32 v206, v211, 2, v206
	v_add_u32_e32 v207, 2048, v206
	v_add_u32_e32 v208, 4096, v206
	v_add_u32_e32 v209, 6144, v206
	s_mov_b32 s76, 0x27402800
	s_lshl_b32 s77, s72, 20
	s_add_u32 s76, s76, s77
	s_lshl_b32 s77, s71, 12
	s_add_u32 s76, s76, s77
	s_add_u32 s62, s94, s76
	s_addc_u32 s63, s95, 0
	s_mov_b32 s76, 0x28403800
	s_lshl_b32 s77, s72, 21
	s_add_u32 s76, s76, s77
	s_lshl_b32 s77, s71, 13
	s_add_u32 s76, s76, s77
	s_add_u32 s64, s94, s76
	s_addc_u32 s65, s95, 0
	s_mov_b32 s76, 0x1a802800
	s_lshl_b32 s77, s74, 23
	s_add_u32 s76, s76, s77
	s_lshl_b32 s77, s71, 15
	s_add_u32 s76, s76, s77
	s_lshl_b32 s77, s75, 9
	s_add_u32 s76, s76, s77
	s_add_u32 s60, s94, s76
	s_addc_u32 s61, s95, 0
	s_mov_b32 s76, 0x23002800
	s_lshl_b32 s77, s72, 22
	s_add_u32 s76, s76, s77
	s_lshl_b32 s77, s73, 19
	s_add_u32 s76, s76, s77
	s_add_u32 s66, s94, s76
	s_addc_u32 s67, s95, 0
	s_mov_b32 s76, 0x2a402800
	s_lshl_b32 s77, s74, 24
	s_add_u32 s76, s76, s77
	s_lshl_b32 s77, s71, 16
	s_add_u32 s76, s76, s77
	s_lshl_b32 s77, s75, 10
	s_add_u32 s76, s76, s77
	s_lshl_b32 s77, s73, 7
	s_add_u32 s76, s76, s77
	s_add_u32 s68, s94, s76
	s_addc_u32 s69, s95, 0
	s_mov_b32 s76, 0x6500000
	s_lshl_b32 s77, s72, 19
	s_add_u32 s76, s76, s77
	s_lshl_b32 s77, s71, 16
	s_add_u32 s76, s76, s77
	s_lshl_b32 s77, s73, 8
	s_add_u32 s76, s76, s77
	s_add_u32 s44, s92, s76
	s_addc_u32 s45, s93, 0
	s_add_u32 s46, s44, 0x8000
	s_addc_u32 s47, s45, 0
	global_load_dwordx4 v[176:179], v194, s[66:67]
	global_load_dwordx4 v[180:183], v194, s[66:67] offset:16
	global_load_dwordx4 v[0:3], v193, s[60:61]
	global_load_dwordx4 v[4:7], v193, s[60:61] offset:64
	global_load_dwordx4 v[8:11], v193, s[60:61] offset:128
	global_load_dwordx4 v[12:15], v193, s[60:61] offset:192
	global_load_dwordx4 v[16:19], v193, s[60:61] offset:256
	global_load_dwordx4 v[20:23], v193, s[60:61] offset:320
	global_load_dwordx4 v[24:27], v193, s[60:61] offset:384
	global_load_dwordx4 v[28:31], v193, s[60:61] offset:448
	global_load_dwordx4 v[32:35], v192, s[62:63]
	global_load_dwordx4 v[36:39], v192, s[62:63] offset:1024
	global_load_dwordx4 v[40:43], v192, s[62:63] offset:2048
	global_load_dwordx4 v[44:47], v192, s[62:63] offset:3072
	global_load_dwordx4 v[48:51], v192, s[64:65] offset:-4096
	global_load_dwordx4 v[64:67], v192, s[64:65]
	global_load_dwordx4 v[52:55], v192, s[64:65] offset:-3072
	global_load_dwordx4 v[68:71], v192, s[64:65] offset:1024
	global_load_dwordx4 v[56:59], v192, s[64:65] offset:-2048
	global_load_dwordx4 v[72:75], v192, s[64:65] offset:2048
	global_load_dwordx4 v[60:63], v192, s[64:65] offset:-1024
	global_load_dwordx4 v[76:79], v192, s[64:65] offset:3072
	v_mov_b32_e32 v216, 0
	v_mov_b32_e32 v217, 0
	v_mov_b32_e32 v218, 0
	v_mov_b32_e32 v219, 0
	v_mov_b32_e32 v80, 0
	v_mov_b32_e32 v81, 0
	v_mov_b32_e32 v82, 0
	v_mov_b32_e32 v83, 0
	v_mov_b32_e32 v84, 0
	v_mov_b32_e32 v85, 0
	v_mov_b32_e32 v86, 0
	v_mov_b32_e32 v87, 0
	v_mov_b32_e32 v88, 0
	v_mov_b32_e32 v89, 0
	v_mov_b32_e32 v90, 0
	v_mov_b32_e32 v91, 0
	v_mov_b32_e32 v92, 0
	v_mov_b32_e32 v93, 0
	v_mov_b32_e32 v94, 0
	v_mov_b32_e32 v95, 0
	v_mov_b32_e32 v96, 0
	v_mov_b32_e32 v97, 0
	v_mov_b32_e32 v98, 0
	v_mov_b32_e32 v99, 0
	v_mov_b32_e32 v100, 0
	v_mov_b32_e32 v101, 0
	v_mov_b32_e32 v102, 0
	v_mov_b32_e32 v103, 0
	v_mov_b32_e32 v104, 0
	v_mov_b32_e32 v105, 0
	v_mov_b32_e32 v106, 0
	v_mov_b32_e32 v107, 0
	v_mov_b32_e32 v108, 0
	v_mov_b32_e32 v109, 0
	v_mov_b32_e32 v110, 0
	v_mov_b32_e32 v111, 0
	v_lshlrev_b32_e32 v213, 4, v198
	ds_write_b128 v213, v[216:219] offset:0
	ds_write_b128 v213, v[216:219] offset:8192
	ds_write_b128 v213, v[216:219] offset:16384
	ds_write_b128 v213, v[216:219] offset:24576
	ds_write_b128 v213, v[216:219] offset:32768
	s_waitcnt vmcnt(20)
	ds_write_b128 v201, v[176:179]
	ds_write_b128 v201, v[180:183] offset:16
	v_add_u32_e32 v201, 17408, v201
	s_add_u32 s60, s60, 0x40000
	s_addc_u32 s61, s61, 0
	s_add_u32 s62, s62, 0x8000
	s_addc_u32 s63, s63, 0
	s_add_u32 s64, s64, 0x10000
	s_addc_u32 s65, s65, 0
	s_add_u32 s66, s66, 0x100
	s_addc_u32 s67, s67, 0
	s_mov_b32 s70, 0
	s_mov_b32 s80, 33792
	s_mov_b32 s81, 17408
	s_waitcnt vmcnt(0) lgkmcnt(0)
	s_barrier
.Lscan_chunk:
	global_load_dwordx4 v[176:179], v194, s[66:67]
	global_load_dwordx4 v[180:183], v194, s[66:67] offset:16
	ds_read_b128 v[144:147], v196 offset:0
	ds_read_b128 v[148:151], v196 offset:8448
	ds_read_b128 v[152:155], v196 offset:16896
	ds_read_b128 v[156:159], v196 offset:25344
	ds_read_b128 v[160:163], v196 offset:64
	ds_read_b128 v[164:167], v196 offset:8512
	ds_read_b128 v[168:171], v196 offset:16960
	s_waitcnt lgkmcnt(6)
	s_waitcnt vmcnt(25)
	v_mfma_f32_16x16x32_bf16 v[112:115], v[144:147], v[0:3], 0
	ds_read_b128 v[172:175], v196 offset:25408
	s_waitcnt lgkmcnt(6)
	v_mfma_f32_16x16x32_bf16 v[116:119], v[148:151], v[0:3], 0
	ds_read_b128 v[144:147], v196 offset:128
	s_waitcnt lgkmcnt(6)
	v_mfma_f32_16x16x32_bf16 v[120:123], v[152:155], v[0:3], 0
	ds_read_b128 v[148:151], v196 offset:8576
	s_waitcnt lgkmcnt(6)
	v_mfma_f32_16x16x32_bf16 v[124:127], v[156:159], v[0:3], 0
	global_load_dwordx4 v[0:3], v193, s[60:61]
	ds_read_b128 v[152:155], v196 offset:17024
	s_waitcnt lgkmcnt(6)
	s_waitcnt vmcnt(25)
	v_mfma_f32_16x16x32_bf16 v[112:115], v[160:163], v[4:7], v[112:115]
	ds_read_b128 v[156:159], v196 offset:25472
	s_waitcnt lgkmcnt(6)
	v_mfma_f32_16x16x32_bf16 v[116:119], v[164:167], v[4:7], v[116:119]
	ds_read_b128 v[160:163], v196 offset:192
	s_waitcnt lgkmcnt(6)
	v_mfma_f32_16x16x32_bf16 v[120:123], v[168:171], v[4:7], v[120:123]
	ds_read_b128 v[164:167], v196 offset:8640
	s_waitcnt lgkmcnt(6)
	v_mfma_f32_16x16x32_bf16 v[124:127], v[172:175], v[4:7], v[124:127]
	global_load_dwordx4 v[4:7], v193, s[60:61] offset:64
	ds_read_b128 v[168:171], v196 offset:17088
	s_waitcnt lgkmcnt(6)
	s_waitcnt vmcnt(25)
	v_mfma_f32_16x16x32_bf16 v[112:115], v[144:147], v[8:11], v[112:115]
	ds_read_b128 v[172:175], v196 offset:25536
	s_waitcnt lgkmcnt(6)
	v_mfma_f32_16x16x32_bf16 v[116:119], v[148:151], v[8:11], v[116:119]
	ds_read_b128 v[144:147], v196 offset:256
	s_waitcnt lgkmcnt(6)
	v_mfma_f32_16x16x32_bf16 v[120:123], v[152:155], v[8:11], v[120:123]
	ds_read_b128 v[148:151], v196 offset:8704
	s_waitcnt lgkmcnt(6)
	v_mfma_f32_16x16x32_bf16 v[124:127], v[156:159], v[8:11], v[124:127]
	global_load_dwordx4 v[8:11], v193, s[60:61] offset:128
	ds_read_b128 v[152:155], v196 offset:17152
	s_waitcnt lgkmcnt(6)
	s_waitcnt vmcnt(25)
	v_mfma_f32_16x16x32_bf16 v[112:115], v[160:163], v[12:15], v[112:115]
	ds_read_b128 v[156:159], v196 offset:25600
	s_waitcnt lgkmcnt(6)
	v_mfma_f32_16x16x32_bf16 v[116:119], v[164:167], v[12:15], v[116:119]
	ds_read_b128 v[160:163], v196 offset:320
	s_waitcnt lgkmcnt(6)
	v_mfma_f32_16x16x32_bf16 v[120:123], v[168:171], v[12:15], v[120:123]
	ds_read_b128 v[164:167], v196 offset:8768
	s_waitcnt lgkmcnt(6)
	v_mfma_f32_16x16x32_bf16 v[124:127], v[172:175], v[12:15], v[124:127]
	global_load_dwordx4 v[12:15], v193, s[60:61] offset:192
	ds_read_b128 v[168:171], v196 offset:17216
	s_waitcnt lgkmcnt(6)
	s_waitcnt vmcnt(25)
	v_mfma_f32_16x16x32_bf16 v[112:115], v[144:147], v[16:19], v[112:115]
	ds_read_b128 v[172:175], v196 offset:25664
	s_waitcnt lgkmcnt(6)
	v_mfma_f32_16x16x32_bf16 v[116:119], v[148:151], v[16:19], v[116:119]
	ds_read_b128 v[144:147], v196 offset:384
	s_waitcnt lgkmcnt(6)
	v_mfma_f32_16x16x32_bf16 v[120:123], v[152:155], v[16:19], v[120:123]
	ds_read_b128 v[148:151], v196 offset:8832
	s_waitcnt lgkmcnt(6)
	v_mfma_f32_16x16x32_bf16 v[124:127], v[156:159], v[16:19], v[124:127]
	global_load_dwordx4 v[16:19], v193, s[60:61] offset:256
	ds_read_b128 v[152:155], v196 offset:17280
	s_waitcnt lgkmcnt(6)
	s_waitcnt vmcnt(25)
	v_mfma_f32_16x16x32_bf16 v[112:115], v[160:163], v[20:23], v[112:115]
	ds_read_b128 v[156:159], v196 offset:25728
	s_waitcnt lgkmcnt(6)
	v_mfma_f32_16x16x32_bf16 v[116:119], v[164:167], v[20:23], v[116:119]
	ds_read_b128 v[160:163], v196 offset:448
	s_waitcnt lgkmcnt(6)
	v_mfma_f32_16x16x32_bf16 v[120:123], v[168:171], v[20:23], v[120:123]
	ds_read_b128 v[164:167], v196 offset:8896
	s_waitcnt lgkmcnt(6)
	v_mfma_f32_16x16x32_bf16 v[124:127], v[172:175], v[20:23], v[124:127]
	global_load_dwordx4 v[20:23], v193, s[60:61] offset:320
	ds_read_b128 v[168:171], v196 offset:17344
	s_waitcnt lgkmcnt(6)
	s_waitcnt vmcnt(25)
	v_mfma_f32_16x16x32_bf16 v[112:115], v[144:147], v[24:27], v[112:115]
	ds_read_b128 v[172:175], v196 offset:25792
	s_waitcnt lgkmcnt(6)
	v_mfma_f32_16x16x32_bf16 v[116:119], v[148:151], v[24:27], v[116:119]
	ds_read_b128 v[144:147], v197 offset:0
	s_waitcnt lgkmcnt(6)
	v_mfma_f32_16x16x32_bf16 v[120:123], v[152:155], v[24:27], v[120:123]
	ds_read_b128 v[148:151], v197 offset:4352
	s_waitcnt lgkmcnt(6)
	v_mfma_f32_16x16x32_bf16 v[124:127], v[156:159], v[24:27], v[124:127]
	global_load_dwordx4 v[24:27], v193, s[60:61] offset:384
	ds_read_b128 v[152:155], v197 offset:8704
	s_waitcnt lgkmcnt(6)
	s_waitcnt vmcnt(25)
	v_mfma_f32_16x16x32_bf16 v[112:115], v[160:163], v[28:31], v[112:115]
	ds_read_b128 v[156:159], v197 offset:13056
	s_waitcnt lgkmcnt(6)
	v_mfma_f32_16x16x32_bf16 v[116:119], v[164:167], v[28:31], v[116:119]
	ds_read_b128 v[160:163], v197 offset:64
	s_waitcnt lgkmcnt(6)
	v_mfma_f32_16x16x32_bf16 v[120:123], v[168:171], v[28:31], v[120:123]
	ds_read_b128 v[164:167], v197 offset:4416
	s_waitcnt lgkmcnt(6)
	v_mfma_f32_16x16x32_bf16 v[124:127], v[172:175], v[28:31], v[124:127]
	global_load_dwordx4 v[28:31], v193, s[60:61] offset:448
	ds_read_b128 v[168:171], v197 offset:8768
	s_waitcnt lgkmcnt(6)
	s_waitcnt vmcnt(25)
	v_mfma_f32_16x16x32_bf16 v[128:131], v[144:147], v[32:35], 0
	ds_read_b128 v[172:175], v197 offset:13120
	s_waitcnt lgkmcnt(6)
	v_mfma_f32_16x16x32_bf16 v[132:135], v[148:151], v[32:35], 0
	ds_read_b128 v[144:147], v197 offset:128
	s_waitcnt lgkmcnt(6)
	v_mfma_f32_16x16x32_bf16 v[136:139], v[152:155], v[32:35], 0
	ds_read_b128 v[148:151], v197 offset:4480
	s_waitcnt lgkmcnt(6)
	v_mfma_f32_16x16x32_bf16 v[140:143], v[156:159], v[32:35], 0
	global_load_dwordx4 v[32:35], v192, s[62:63]
	ds_read_b128 v[152:155], v197 offset:8832
	s_waitcnt lgkmcnt(6)
	s_waitcnt vmcnt(25)
	v_mfma_f32_16x16x32_bf16 v[128:131], v[160:163], v[36:39], v[128:131]
	ds_read_b128 v[156:159], v197 offset:13184
	s_waitcnt lgkmcnt(6)
	v_mfma_f32_16x16x32_bf16 v[132:135], v[164:167], v[36:39], v[132:135]
	ds_read_b128 v[160:163], v197 offset:192
	s_waitcnt lgkmcnt(6)
	v_mfma_f32_16x16x32_bf16 v[136:139], v[168:171], v[36:39], v[136:139]
	ds_read_b128 v[164:167], v197 offset:4544
	s_waitcnt lgkmcnt(6)
	v_mfma_f32_16x16x32_bf16 v[140:143], v[172:175], v[36:39], v[140:143]
	global_load_dwordx4 v[36:39], v192, s[62:63] offset:1024
	ds_read_b128 v[168:171], v197 offset:8896
	s_waitcnt lgkmcnt(6)
	s_waitcnt vmcnt(25)
	v_mfma_f32_16x16x32_bf16 v[128:131], v[144:147], v[40:43], v[128:131]
	ds_read_b128 v[172:175], v197 offset:13248
	s_waitcnt lgkmcnt(6)
	v_mfma_f32_16x16x32_bf16 v[132:135], v[148:151], v[40:43], v[132:135]
	s_waitcnt lgkmcnt(5)
	v_mfma_f32_16x16x32_bf16 v[136:139], v[152:155], v[40:43], v[136:139]
	s_waitcnt lgkmcnt(4)
	v_mfma_f32_16x16x32_bf16 v[140:143], v[156:159], v[40:43], v[140:143]
	global_load_dwordx4 v[40:43], v192, s[62:63] offset:2048
	s_waitcnt lgkmcnt(3)
	s_waitcnt vmcnt(25)
	v_mfma_f32_16x16x32_bf16 v[128:131], v[160:163], v[44:47], v[128:131]
	s_waitcnt lgkmcnt(2)
	v_mfma_f32_16x16x32_bf16 v[132:135], v[164:167], v[44:47], v[132:135]
	s_waitcnt lgkmcnt(1)
	v_mfma_f32_16x16x32_bf16 v[136:139], v[168:171], v[44:47], v[136:139]
	s_waitcnt lgkmcnt(0)
	v_mfma_f32_16x16x32_bf16 v[140:143], v[172:175], v[44:47], v[140:143]
	global_load_dwordx4 v[44:47], v192, s[62:63] offset:3072
	s_nop 7
	v_pk_fma_f32 v[112:113], v[112:113], v[202:203], v[128:129]
	v_pk_fma_f32 v[114:115], v[114:115], v[202:203], v[130:131]
	v_pk_fma_f32 v[116:117], v[116:117], v[202:203], v[132:133]
	v_pk_fma_f32 v[118:119], v[118:119], v[202:203], v[134:135]
	v_pk_fma_f32 v[120:121], v[120:121], v[202:203], v[136:137]
	v_pk_fma_f32 v[122:123], v[122:123], v[202:203], v[138:139]
	v_pk_fma_f32 v[124:125], v[124:125], v[202:203], v[140:141]
	v_pk_fma_f32 v[126:127], v[126:127], v[202:203], v[142:143]
	v_cvt_pk_bf16_f32 v184, v112, v113
	v_cvt_pk_bf16_f32 v185, v114, v115
	v_cvt_pk_bf16_f32 v186, v116, v117
	v_cvt_pk_bf16_f32 v187, v118, v119
	v_cvt_pk_bf16_f32 v188, v120, v121
	v_cvt_pk_bf16_f32 v189, v122, v123
	v_cvt_pk_bf16_f32 v190, v124, v125
	v_cvt_pk_bf16_f32 v191, v126, v127
	global_store_dwordx2 v195, v[184:185], s[68:69]
	global_store_dwordx2 v195, v[186:187], s[68:69] offset:32
	global_store_dwordx2 v195, v[188:189], s[68:69] offset:64
	global_store_dwordx2 v195, v[190:191], s[68:69] offset:96
	v_pk_mul_f32 v[80:81], v[80:81], v[204:205]
	v_pk_mul_f32 v[82:83], v[82:83], v[204:205]
	v_pk_mul_f32 v[84:85], v[84:85], v[204:205]
	v_pk_mul_f32 v[86:87], v[86:87], v[204:205]
	v_pk_mul_f32 v[88:89], v[88:89], v[204:205]
	v_pk_mul_f32 v[90:91], v[90:91], v[204:205]
	v_pk_mul_f32 v[92:93], v[92:93], v[204:205]
	v_pk_mul_f32 v[94:95], v[94:95], v[204:205]
	v_pk_mul_f32 v[96:97], v[96:97], v[204:205]
	v_pk_mul_f32 v[98:99], v[98:99], v[204:205]
	v_pk_mul_f32 v[100:101], v[100:101], v[204:205]
	v_pk_mul_f32 v[102:103], v[102:103], v[204:205]
	v_pk_mul_f32 v[104:105], v[104:105], v[204:205]
	v_pk_mul_f32 v[106:107], v[106:107], v[204:205]
	v_pk_mul_f32 v[108:109], v[108:109], v[204:205]
	v_pk_mul_f32 v[110:111], v[110:111], v[204:205]
	ds_read_b128 v[144:147], v197 offset:0
	ds_read_b128 v[148:151], v197 offset:4352
	ds_read_b128 v[152:155], v197 offset:8704
	ds_read_b128 v[156:159], v197 offset:13056
	ds_read_b128 v[160:163], v197 offset:64
	ds_read_b128 v[164:167], v197 offset:4416
	ds_read_b128 v[168:171], v197 offset:8768
	s_waitcnt lgkmcnt(6)
	s_waitcnt vmcnt(24)
	v_mfma_f32_16x16x32_bf16 v[80:83], v[48:51], v[144:147], v[80:83]
	v_mfma_f32_16x16x32_bf16 v[96:99], v[64:67], v[144:147], v[96:99]
	ds_read_b128 v[172:175], v197 offset:13120
	s_waitcnt lgkmcnt(6)
	v_mfma_f32_16x16x32_bf16 v[84:87], v[48:51], v[148:151], v[84:87]
	v_mfma_f32_16x16x32_bf16 v[100:103], v[64:67], v[148:151], v[100:103]
	ds_read_b128 v[144:147], v197 offset:128
	s_waitcnt lgkmcnt(6)
	v_mfma_f32_16x16x32_bf16 v[88:91], v[48:51], v[152:155], v[88:91]
	v_mfma_f32_16x16x32_bf16 v[104:107], v[64:67], v[152:155], v[104:107]
	ds_read_b128 v[148:151], v197 offset:4480
	s_waitcnt lgkmcnt(6)
	v_mfma_f32_16x16x32_bf16 v[92:95], v[48:51], v[156:159], v[92:95]
	v_mfma_f32_16x16x32_bf16 v[108:111], v[64:67], v[156:159], v[108:111]
	global_load_dwordx4 v[48:51], v192, s[64:65] offset:-4096
	global_load_dwordx4 v[64:67], v192, s[64:65]
	ds_read_b128 v[152:155], v197 offset:8832
	s_waitcnt lgkmcnt(6)
	s_waitcnt vmcnt(24)
	v_mfma_f32_16x16x32_bf16 v[80:83], v[52:55], v[160:163], v[80:83]
	v_mfma_f32_16x16x32_bf16 v[96:99], v[68:71], v[160:163], v[96:99]
	ds_read_b128 v[156:159], v197 offset:13184
	s_waitcnt lgkmcnt(6)
	v_mfma_f32_16x16x32_bf16 v[84:87], v[52:55], v[164:167], v[84:87]
	v_mfma_f32_16x16x32_bf16 v[100:103], v[68:71], v[164:167], v[100:103]
	ds_read_b128 v[160:163], v197 offset:192
	s_waitcnt lgkmcnt(6)
	v_mfma_f32_16x16x32_bf16 v[88:91], v[52:55], v[168:171], v[88:91]
	v_mfma_f32_16x16x32_bf16 v[104:107], v[68:71], v[168:171], v[104:107]
	ds_read_b128 v[164:167], v197 offset:4544
	s_waitcnt lgkmcnt(6)
	v_mfma_f32_16x16x32_bf16 v[92:95], v[52:55], v[172:175], v[92:95]
	v_mfma_f32_16x16x32_bf16 v[108:111], v[68:71], v[172:175], v[108:111]
	global_load_dwordx4 v[52:55], v192, s[64:65] offset:-3072
	global_load_dwordx4 v[68:71], v192, s[64:65] offset:1024
	ds_read_b128 v[168:171], v197 offset:8896
	s_waitcnt lgkmcnt(6)
	s_waitcnt vmcnt(24)
	v_mfma_f32_16x16x32_bf16 v[80:83], v[56:59], v[144:147], v[80:83]
	v_mfma_f32_16x16x32_bf16 v[96:99], v[72:75], v[144:147], v[96:99]
	ds_read_b128 v[172:175], v197 offset:13248
	s_waitcnt lgkmcnt(6)
	v_mfma_f32_16x16x32_bf16 v[84:87], v[56:59], v[148:151], v[84:87]
	v_mfma_f32_16x16x32_bf16 v[100:103], v[72:75], v[148:151], v[100:103]
	s_waitcnt lgkmcnt(5)
	v_mfma_f32_16x16x32_bf16 v[88:91], v[56:59], v[152:155], v[88:91]
	v_mfma_f32_16x16x32_bf16 v[104:107], v[72:75], v[152:155], v[104:107]
	s_waitcnt lgkmcnt(4)
	v_mfma_f32_16x16x32_bf16 v[92:95], v[56:59], v[156:159], v[92:95]
	v_mfma_f32_16x16x32_bf16 v[108:111], v[72:75], v[156:159], v[108:111]
	global_load_dwordx4 v[56:59], v192, s[64:65] offset:-2048
	global_load_dwordx4 v[72:75], v192, s[64:65] offset:2048
	s_waitcnt lgkmcnt(3)
	s_waitcnt vmcnt(24)
	v_mfma_f32_16x16x32_bf16 v[80:83], v[60:63], v[160:163], v[80:83]
	v_mfma_f32_16x16x32_bf16 v[96:99], v[76:79], v[160:163], v[96:99]
	s_waitcnt lgkmcnt(2)
	v_mfma_f32_16x16x32_bf16 v[84:87], v[60:63], v[164:167], v[84:87]
	v_mfma_f32_16x16x32_bf16 v[100:103], v[76:79], v[164:167], v[100:103]
	s_waitcnt lgkmcnt(1)
	v_mfma_f32_16x16x32_bf16 v[88:91], v[60:63], v[168:171], v[88:91]
	v_mfma_f32_16x16x32_bf16 v[104:107], v[76:79], v[168:171], v[104:107]
	s_waitcnt lgkmcnt(0)
	v_mfma_f32_16x16x32_bf16 v[92:95], v[60:63], v[172:175], v[92:95]
	v_mfma_f32_16x16x32_bf16 v[108:111], v[76:79], v[172:175], v[108:111]
	global_load_dwordx4 v[60:63], v192, s[64:65] offset:-1024
	global_load_dwordx4 v[76:79], v192, s[64:65] offset:3072
	s_nop 7
	v_cvt_pk_bf16_f32 v144, v80, v81
	v_cvt_pk_bf16_f32 v145, v82, v83
	ds_write_b64 v200, v[144:145] offset:0
	v_cvt_pk_bf16_f32 v148, v84, v85
	v_cvt_pk_bf16_f32 v149, v86, v87
	ds_write_b64 v200, v[148:149] offset:8448
	v_cvt_pk_bf16_f32 v152, v88, v89
	v_cvt_pk_bf16_f32 v153, v90, v91
	ds_write_b64 v200, v[152:153] offset:16896
	v_cvt_pk_bf16_f32 v156, v92, v93
	v_cvt_pk_bf16_f32 v157, v94, v95
	ds_write_b64 v200, v[156:157] offset:25344
	v_cvt_pk_bf16_f32 v160, v96, v97
	v_cvt_pk_bf16_f32 v161, v98, v99
	ds_write_b64 v200, v[160:161] offset:32
	v_cvt_pk_bf16_f32 v164, v100, v101
	v_cvt_pk_bf16_f32 v165, v102, v103
	ds_write_b64 v200, v[164:165] offset:8480
	v_cvt_pk_bf16_f32 v168, v104, v105
	v_cvt_pk_bf16_f32 v169, v106, v107
	ds_write_b64 v200, v[168:169] offset:16928
	v_cvt_pk_bf16_f32 v172, v108, v109
	v_cvt_pk_bf16_f32 v173, v110, v111
	ds_write_b64 v200, v[172:173] offset:25376
	s_waitcnt vmcnt(24)
	ds_write_b128 v201, v[176:179]
	ds_write_b128 v201, v[180:183] offset:16
	v_add_u32_e32 v196, s80, v196
	v_subrev_u32_e32 v200, s80, v200
	v_add_u32_e32 v197, s81, v197
	v_subrev_u32_e32 v201, s81, v201
	s_sub_u32 s80, 0, s80
	s_sub_u32 s81, 0, s81
	s_add_u32 s68, s68, 0x80000
	s_addc_u32 s69, s69, 0
	s_add_u32 s70, s70, 1
	s_cmp_lt_u32 s70, 31
	s_cselect_b32 s83, 1, 0
	s_lshl_b32 s76, s83, 18
	s_add_u32 s60, s60, s76
	s_addc_u32 s61, s61, 0
	s_lshl_b32 s76, s83, 15
	s_add_u32 s62, s62, s76
	s_addc_u32 s63, s63, 0
	s_lshl_b32 s76, s83, 16
	s_add_u32 s64, s64, s76
	s_addc_u32 s65, s65, 0
	s_lshl_b32 s76, s83, 8
	s_add_u32 s66, s66, s76
	s_addc_u32 s67, s67, 0
	s_waitcnt lgkmcnt(0)
	s_barrier
	s_cmp_lt_u32 s70, 32
	s_cbranch_scc1 .Lscan_chunk
	s_waitcnt vmcnt(0)
	global_store_dword v206, v80, s[44:45]
	global_store_dword v207, v81, s[44:45]
	global_store_dword v208, v82, s[44:45]
	global_store_dword v209, v83, s[44:45]
	global_store_dword v206, v84, s[44:45] offset:64
	global_store_dword v207, v85, s[44:45] offset:64
	global_store_dword v208, v86, s[44:45] offset:64
	global_store_dword v209, v87, s[44:45] offset:64
	global_store_dword v206, v88, s[44:45] offset:128
	global_store_dword v207, v89, s[44:45] offset:128
	global_store_dword v208, v90, s[44:45] offset:128
	global_store_dword v209, v91, s[44:45] offset:128
	global_store_dword v206, v92, s[44:45] offset:192
	global_store_dword v207, v93, s[44:45] offset:192
	global_store_dword v208, v94, s[44:45] offset:192
	global_store_dword v209, v95, s[44:45] offset:192
	global_store_dword v206, v96, s[46:47]
	global_store_dword v207, v97, s[46:47]
	global_store_dword v208, v98, s[46:47]
	global_store_dword v209, v99, s[46:47]
	global_store_dword v206, v100, s[46:47] offset:64
	global_store_dword v207, v101, s[46:47] offset:64
	global_store_dword v208, v102, s[46:47] offset:64
	global_store_dword v209, v103, s[46:47] offset:64
	global_store_dword v206, v104, s[46:47] offset:128
	global_store_dword v207, v105, s[46:47] offset:128
	global_store_dword v208, v106, s[46:47] offset:128
	global_store_dword v209, v107, s[46:47] offset:128
	global_store_dword v206, v108, s[46:47] offset:192
	global_store_dword v207, v109, s[46:47] offset:192
	global_store_dword v208, v110, s[46:47] offset:192
	global_store_dword v209, v111, s[46:47] offset:192
